# filter-spectra k-loop: H3 rows loaded coalesced (1 KiB per instruction), per-lane partial dot products reduced with DPP row_ror, handed to the row owner through a per-wave LDS scratch; f32 throughout,
# speedup vs baseline: 1.1024x; 1.0118x over previous
; template <int L, int N> DEVQ void filt_item(const Params& P, LAS unsigned char* lds, const float* H3v, int d, cf* specd, float* cornerd) {
;     ...
;     const float delta = fabsf(MIN_DECAY + (float)d * ((MAX_DECAY - MIN_DECAY) / 1023.0f));
;     const float invN = 1.0f / (float)N;
;     for (int k = tid; k < L; k += NTHR) {
;         asm volatile("" ::: "memory");
;         const f32x4* hr = (const f32x4*)(H3v + (size_t)k * 64);
;         f32x4 acc = (f32x4){0.f, 0.f, 0.f, 0.f};
;         f32x4 hv[16];
; #pragma unroll
;         for (int i4 = 0; i4 < 16; ++i4) hv[i4] = hr[i4];
; #pragma unroll
;         for (int i4 = 0; i4 < 16; ++i4) { if ((i4 & 3) == 0) asm volatile("" ::: "memory");
;             acc += hv[i4].x * wc4[4 * i4] + hv[i4].y * wc4[4 * i4 + 1] + hv[i4].z * wc4[4 * i4 + 2] + hv[i4].w * wc4[4 * i4 + 3]; }
.LBB0_588:
	s_or_b64 exec, exec, s[0:1]
	v_cmp_gt_i32_e32 vcc, s16, v64
	s_waitcnt lgkmcnt(0)
	s_barrier
	s_and_saveexec_b64 s[0:1], vcc
	s_cbranch_execz .LBB0_597
	s_waitcnt vmcnt(0)
	v_cvt_f32_i32_e32 v2, s10
	v_readlane_b32 s2, v253, 41
	v_lshlrev_b64 v[0:1], 8, v[64:65]
	v_mov_b32_e32 v3, 0xc0447cbd
	v_lshl_add_u32 v72, v64, 2, s2
	v_readlane_b32 s2, v255, 40
	v_readlane_b32 s3, v255, 41
	v_sub_u32_e32 v73, 0x2000, v64
	v_fmamk_f32 v74, v2, 0xbc44ade8, v3
	v_lshl_add_u64 v[66:67], s[2:3], 0, v[0:1]
	s_mov_b64 s[12:13], 0
	v_mov_b32_e32 v75, v64
	v_mbcnt_lo_u32_b32 v202, -1, 0
	v_mbcnt_hi_u32_b32 v202, -1, v202
	v_mul_u32_u24_e32 v203, 0xf0, v202
	v_sub_u32_e32 v248, 0x1000, v203
	v_sub_u32_e32 v246, 0x3000, v203
	v_ashrrev_i32_e32 v249, 31, v248
	v_ashrrev_i32_e32 v247, 31, v246
	v_and_b32_e32 v203, 15, v202
	v_lshl_add_u32 v203, v203, 6, 0
	v_add_u32_e32 v203, 0x20000, v203
	ds_read_b128 v[148:151], v203
	ds_read_b128 v[154:157], v203 offset:16
	ds_read_b128 v[158:161], v203 offset:32
	ds_read_b128 v[162:165], v203 offset:48
	v_lshrrev_b32_e32 v204, 6, v64
	v_cmp_lt_u32_e64 s[2:3], 5, v204
	v_lshl_add_u32 v204, v204, 10, 0
	v_mov_b32_e32 v205, 0x400
	v_add_u32_e32 v204, 0x20800, v204
	v_cndmask_b32_e64 v205, 0, v205, s[2:3]
	v_add_u32_e32 v204, v204, v205
	v_lshrrev_b32_e32 v205, 4, v202
	v_lshl_add_u32 v251, v205, 4, v204
	v_lshl_add_u32 v250, v202, 4, v204
	s_waitcnt lgkmcnt(0)
	s_branch .LBB0_591

; template <int L, int N> DEVQ void filt_item(const Params& P, LAS unsigned char* lds, const float* H3v, int d, cf* specd, float* cornerd) {
;     ...
;         const f32x4* hr = (const f32x4*)(H3v + (size_t)k * 64);
;         f32x4 acc = (f32x4){0.f, 0.f, 0.f, 0.f};
;         f32x4 hv[16];
; #pragma unroll
;         for (int i4 = 0; i4 < 16; ++i4) hv[i4] = hr[i4];
; #pragma unroll
;         for (int i4 = 0; i4 < 16; ++i4) { if ((i4 & 3) == 0) asm volatile("" ::: "memory");
;             acc += hv[i4].x * wc4[4 * i4] + hv[i4].y * wc4[4 * i4 + 1] + hv[i4].z * wc4[4 * i4 + 2] + hv[i4].w * wc4[4 * i4 + 3]; }
.LBB0_591:
	s_mov_b64 s[14:15], exec
	s_mov_b64 exec, -1
	v_lshl_add_u64 v[198:199], v[66:67], 0, v[248:249]
	v_lshl_add_u64 v[200:201], v[66:67], 0, v[246:247]
	global_load_dwordx4 v[0:3], v[198:199], off offset:-4096
	global_load_dwordx4 v[4:7], v[198:199], off offset:-3072
	global_load_dwordx4 v[8:11], v[198:199], off offset:-2048
	global_load_dwordx4 v[12:15], v[198:199], off offset:-1024
	global_load_dwordx4 v[16:19], v[198:199], off offset:0
	global_load_dwordx4 v[20:23], v[198:199], off offset:1024
	global_load_dwordx4 v[24:27], v[198:199], off offset:2048
	global_load_dwordx4 v[28:31], v[198:199], off offset:3072
	global_load_dwordx4 v[32:35], v[200:201], off offset:-4096
	global_load_dwordx4 v[36:39], v[200:201], off offset:-3072
	global_load_dwordx4 v[40:43], v[200:201], off offset:-2048
	global_load_dwordx4 v[44:47], v[200:201], off offset:-1024
	global_load_dwordx4 v[48:51], v[200:201], off offset:0
	global_load_dwordx4 v[52:55], v[200:201], off offset:1024
	global_load_dwordx4 v[56:59], v[200:201], off offset:2048
	global_load_dwordx4 v[60:63], v[200:201], off offset:3072
	s_mov_b32 s2, 0x10001
	s_mov_b32 s3, 0x10001
	s_waitcnt vmcnt(15)
	v_mul_f32_e32 v194, v0, v148
	v_mul_f32_e32 v195, v0, v149
	v_mul_f32_e32 v196, v0, v150
	v_mul_f32_e32 v197, v0, v151
	v_fmac_f32_e32 v194, v1, v154
	v_fmac_f32_e32 v195, v1, v155
	v_fmac_f32_e32 v196, v1, v156
	v_fmac_f32_e32 v197, v1, v157
	v_fmac_f32_e32 v194, v2, v158
	v_fmac_f32_e32 v195, v2, v159
	v_fmac_f32_e32 v196, v2, v160
	v_fmac_f32_e32 v197, v2, v161
	v_fmac_f32_e32 v194, v3, v162
	v_fmac_f32_e32 v195, v3, v163
	v_fmac_f32_e32 v196, v3, v164
	v_fmac_f32_e32 v197, v3, v165
	v_add_f32_dpp v194, v194, v194 row_ror:8 row_mask:0xf bank_mask:0xf
	v_add_f32_dpp v195, v195, v195 row_ror:8 row_mask:0xf bank_mask:0xf
	v_add_f32_dpp v196, v196, v196 row_ror:8 row_mask:0xf bank_mask:0xf
	v_add_f32_dpp v197, v197, v197 row_ror:8 row_mask:0xf bank_mask:0xf
	v_add_f32_dpp v194, v194, v194 row_ror:4 row_mask:0xf bank_mask:0xf
	v_add_f32_dpp v195, v195, v195 row_ror:4 row_mask:0xf bank_mask:0xf
	v_add_f32_dpp v196, v196, v196 row_ror:4 row_mask:0xf bank_mask:0xf
	v_add_f32_dpp v197, v197, v197 row_ror:4 row_mask:0xf bank_mask:0xf
	v_add_f32_dpp v194, v194, v194 row_ror:2 row_mask:0xf bank_mask:0xf
	v_add_f32_dpp v195, v195, v195 row_ror:2 row_mask:0xf bank_mask:0xf
	v_add_f32_dpp v196, v196, v196 row_ror:2 row_mask:0xf bank_mask:0xf
	v_add_f32_dpp v197, v197, v197 row_ror:2 row_mask:0xf bank_mask:0xf
	v_add_f32_dpp v194, v194, v194 row_ror:1 row_mask:0xf bank_mask:0xf
	v_add_f32_dpp v195, v195, v195 row_ror:1 row_mask:0xf bank_mask:0xf
	v_add_f32_dpp v196, v196, v196 row_ror:1 row_mask:0xf bank_mask:0xf
	v_add_f32_dpp v197, v197, v197 row_ror:1 row_mask:0xf bank_mask:0xf
	s_mov_b64 exec, s[2:3]
	ds_write_b128 v251, v[194:197]
	s_mov_b64 exec, -1
	s_waitcnt vmcnt(14)
	v_mul_f32_e32 v210, v4, v148
	v_mul_f32_e32 v211, v4, v149
	v_mul_f32_e32 v212, v4, v150
	v_mul_f32_e32 v213, v4, v151
	v_fmac_f32_e32 v210, v5, v154
	v_fmac_f32_e32 v211, v5, v155
	v_fmac_f32_e32 v212, v5, v156
	v_fmac_f32_e32 v213, v5, v157
	v_fmac_f32_e32 v210, v6, v158
	v_fmac_f32_e32 v211, v6, v159
	v_fmac_f32_e32 v212, v6, v160
	v_fmac_f32_e32 v213, v6, v161
	v_fmac_f32_e32 v210, v7, v162
	v_fmac_f32_e32 v211, v7, v163
	v_fmac_f32_e32 v212, v7, v164
	v_fmac_f32_e32 v213, v7, v165
	v_add_f32_dpp v210, v210, v210 row_ror:8 row_mask:0xf bank_mask:0xf
	v_add_f32_dpp v211, v211, v211 row_ror:8 row_mask:0xf bank_mask:0xf
	v_add_f32_dpp v212, v212, v212 row_ror:8 row_mask:0xf bank_mask:0xf
	v_add_f32_dpp v213, v213, v213 row_ror:8 row_mask:0xf bank_mask:0xf
	v_add_f32_dpp v210, v210, v210 row_ror:4 row_mask:0xf bank_mask:0xf
	v_add_f32_dpp v211, v211, v211 row_ror:4 row_mask:0xf bank_mask:0xf
	v_add_f32_dpp v212, v212, v212 row_ror:4 row_mask:0xf bank_mask:0xf
	v_add_f32_dpp v213, v213, v213 row_ror:4 row_mask:0xf bank_mask:0xf
	v_add_f32_dpp v210, v210, v210 row_ror:2 row_mask:0xf bank_mask:0xf
	v_add_f32_dpp v211, v211, v211 row_ror:2 row_mask:0xf bank_mask:0xf
	v_add_f32_dpp v212, v212, v212 row_ror:2 row_mask:0xf bank_mask:0xf
	v_add_f32_dpp v213, v213, v213 row_ror:2 row_mask:0xf bank_mask:0xf
	v_add_f32_dpp v210, v210, v210 row_ror:1 row_mask:0xf bank_mask:0xf
	v_add_f32_dpp v211, v211, v211 row_ror:1 row_mask:0xf bank_mask:0xf
	v_add_f32_dpp v212, v212, v212 row_ror:1 row_mask:0xf bank_mask:0xf
	v_add_f32_dpp v213, v213, v213 row_ror:1 row_mask:0xf bank_mask:0xf
	s_mov_b64 exec, s[2:3]
	ds_write_b128 v251, v[210:213] offset:64
	s_mov_b64 exec, -1
	s_waitcnt vmcnt(13)
	v_mul_f32_e32 v194, v8, v148
	v_mul_f32_e32 v195, v8, v149
	v_mul_f32_e32 v196, v8, v150
	v_mul_f32_e32 v197, v8, v151
	v_fmac_f32_e32 v194, v9, v154
	v_fmac_f32_e32 v195, v9, v155
	v_fmac_f32_e32 v196, v9, v156
	v_fmac_f32_e32 v197, v9, v157
	v_fmac_f32_e32 v194, v10, v158
	v_fmac_f32_e32 v195, v10, v159
	v_fmac_f32_e32 v196, v10, v160
	v_fmac_f32_e32 v197, v10, v161
	v_fmac_f32_e32 v194, v11, v162
	v_fmac_f32_e32 v195, v11, v163
	v_fmac_f32_e32 v196, v11, v164
	v_fmac_f32_e32 v197, v11, v165
	v_add_f32_dpp v194, v194, v194 row_ror:8 row_mask:0xf bank_mask:0xf
	v_add_f32_dpp v195, v195, v195 row_ror:8 row_mask:0xf bank_mask:0xf
	v_add_f32_dpp v196, v196, v196 row_ror:8 row_mask:0xf bank_mask:0xf
	v_add_f32_dpp v197, v197, v197 row_ror:8 row_mask:0xf bank_mask:0xf
	v_add_f32_dpp v194, v194, v194 row_ror:4 row_mask:0xf bank_mask:0xf
	v_add_f32_dpp v195, v195, v195 row_ror:4 row_mask:0xf bank_mask:0xf
	v_add_f32_dpp v196, v196, v196 row_ror:4 row_mask:0xf bank_mask:0xf
	v_add_f32_dpp v197, v197, v197 row_ror:4 row_mask:0xf bank_mask:0xf
	v_add_f32_dpp v194, v194, v194 row_ror:2 row_mask:0xf bank_mask:0xf
	v_add_f32_dpp v195, v195, v195 row_ror:2 row_mask:0xf bank_mask:0xf
	v_add_f32_dpp v196, v196, v196 row_ror:2 row_mask:0xf bank_mask:0xf
	v_add_f32_dpp v197, v197, v197 row_ror:2 row_mask:0xf bank_mask:0xf
	v_add_f32_dpp v194, v194, v194 row_ror:1 row_mask:0xf bank_mask:0xf
	v_add_f32_dpp v195, v195, v195 row_ror:1 row_mask:0xf bank_mask:0xf
	v_add_f32_dpp v196, v196, v196 row_ror:1 row_mask:0xf bank_mask:0xf
	v_add_f32_dpp v197, v197, v197 row_ror:1 row_mask:0xf bank_mask:0xf
	s_mov_b64 exec, s[2:3]
	ds_write_b128 v251, v[194:197] offset:128
	s_mov_b64 exec, -1
	s_waitcnt vmcnt(12)
; template <int L, int N> DEVQ void filt_item(const Params& P, LAS unsigned char* lds, const float* H3v, int d, cf* specd, float* cornerd) {
;     ...
;         for (int i4 = 0; i4 < 16; ++i4) hv[i4] = hr[i4];
; #pragma unroll
;         for (int i4 = 0; i4 < 16; ++i4) { if ((i4 & 3) == 0) asm volatile("" ::: "memory");
;             acc += hv[i4].x * wc4[4 * i4] + hv[i4].y * wc4[4 * i4 + 1] + hv[i4].z * wc4[4 * i4 + 2] + hv[i4].w * wc4[4 * i4 + 3]; }
	v_mul_f32_e32 v210, v12, v148
	v_mul_f32_e32 v211, v12, v149
	v_mul_f32_e32 v212, v12, v150
	v_mul_f32_e32 v213, v12, v151
	v_fmac_f32_e32 v210, v13, v154
	v_fmac_f32_e32 v211, v13, v155
	v_fmac_f32_e32 v212, v13, v156
	v_fmac_f32_e32 v213, v13, v157
	v_fmac_f32_e32 v210, v14, v158
	v_fmac_f32_e32 v211, v14, v159
	v_fmac_f32_e32 v212, v14, v160
	v_fmac_f32_e32 v213, v14, v161
	v_fmac_f32_e32 v210, v15, v162
	v_fmac_f32_e32 v211, v15, v163
	v_fmac_f32_e32 v212, v15, v164
	v_fmac_f32_e32 v213, v15, v165
	v_add_f32_dpp v210, v210, v210 row_ror:8 row_mask:0xf bank_mask:0xf
	v_add_f32_dpp v211, v211, v211 row_ror:8 row_mask:0xf bank_mask:0xf
	v_add_f32_dpp v212, v212, v212 row_ror:8 row_mask:0xf bank_mask:0xf
	v_add_f32_dpp v213, v213, v213 row_ror:8 row_mask:0xf bank_mask:0xf
	v_add_f32_dpp v210, v210, v210 row_ror:4 row_mask:0xf bank_mask:0xf
	v_add_f32_dpp v211, v211, v211 row_ror:4 row_mask:0xf bank_mask:0xf
	v_add_f32_dpp v212, v212, v212 row_ror:4 row_mask:0xf bank_mask:0xf
	v_add_f32_dpp v213, v213, v213 row_ror:4 row_mask:0xf bank_mask:0xf
	v_add_f32_dpp v210, v210, v210 row_ror:2 row_mask:0xf bank_mask:0xf
	v_add_f32_dpp v211, v211, v211 row_ror:2 row_mask:0xf bank_mask:0xf
	v_add_f32_dpp v212, v212, v212 row_ror:2 row_mask:0xf bank_mask:0xf
	v_add_f32_dpp v213, v213, v213 row_ror:2 row_mask:0xf bank_mask:0xf
	v_add_f32_dpp v210, v210, v210 row_ror:1 row_mask:0xf bank_mask:0xf
	v_add_f32_dpp v211, v211, v211 row_ror:1 row_mask:0xf bank_mask:0xf
	v_add_f32_dpp v212, v212, v212 row_ror:1 row_mask:0xf bank_mask:0xf
	v_add_f32_dpp v213, v213, v213 row_ror:1 row_mask:0xf bank_mask:0xf
	s_mov_b64 exec, s[2:3]
	ds_write_b128 v251, v[210:213] offset:192
	s_mov_b64 exec, -1
	s_waitcnt vmcnt(11)
	v_mul_f32_e32 v194, v16, v148
	v_mul_f32_e32 v195, v16, v149
	v_mul_f32_e32 v196, v16, v150
	v_mul_f32_e32 v197, v16, v151
	v_fmac_f32_e32 v194, v17, v154
	v_fmac_f32_e32 v195, v17, v155
	v_fmac_f32_e32 v196, v17, v156
	v_fmac_f32_e32 v197, v17, v157
	v_fmac_f32_e32 v194, v18, v158
	v_fmac_f32_e32 v195, v18, v159
	v_fmac_f32_e32 v196, v18, v160
	v_fmac_f32_e32 v197, v18, v161
	v_fmac_f32_e32 v194, v19, v162
	v_fmac_f32_e32 v195, v19, v163
	v_fmac_f32_e32 v196, v19, v164
	v_fmac_f32_e32 v197, v19, v165
	v_add_f32_dpp v194, v194, v194 row_ror:8 row_mask:0xf bank_mask:0xf
	v_add_f32_dpp v195, v195, v195 row_ror:8 row_mask:0xf bank_mask:0xf
	v_add_f32_dpp v196, v196, v196 row_ror:8 row_mask:0xf bank_mask:0xf
	v_add_f32_dpp v197, v197, v197 row_ror:8 row_mask:0xf bank_mask:0xf
	v_add_f32_dpp v194, v194, v194 row_ror:4 row_mask:0xf bank_mask:0xf
	v_add_f32_dpp v195, v195, v195 row_ror:4 row_mask:0xf bank_mask:0xf
	v_add_f32_dpp v196, v196, v196 row_ror:4 row_mask:0xf bank_mask:0xf
	v_add_f32_dpp v197, v197, v197 row_ror:4 row_mask:0xf bank_mask:0xf
	v_add_f32_dpp v194, v194, v194 row_ror:2 row_mask:0xf bank_mask:0xf
	v_add_f32_dpp v195, v195, v195 row_ror:2 row_mask:0xf bank_mask:0xf
	v_add_f32_dpp v196, v196, v196 row_ror:2 row_mask:0xf bank_mask:0xf
	v_add_f32_dpp v197, v197, v197 row_ror:2 row_mask:0xf bank_mask:0xf
	v_add_f32_dpp v194, v194, v194 row_ror:1 row_mask:0xf bank_mask:0xf
	v_add_f32_dpp v195, v195, v195 row_ror:1 row_mask:0xf bank_mask:0xf
	v_add_f32_dpp v196, v196, v196 row_ror:1 row_mask:0xf bank_mask:0xf
	v_add_f32_dpp v197, v197, v197 row_ror:1 row_mask:0xf bank_mask:0xf
	s_mov_b64 exec, s[2:3]
	ds_write_b128 v251, v[194:197] offset:256
	s_mov_b64 exec, -1
	s_waitcnt vmcnt(10)
	v_mul_f32_e32 v210, v20, v148
	v_mul_f32_e32 v211, v20, v149
	v_mul_f32_e32 v212, v20, v150
	v_mul_f32_e32 v213, v20, v151
	v_fmac_f32_e32 v210, v21, v154
	v_fmac_f32_e32 v211, v21, v155
	v_fmac_f32_e32 v212, v21, v156
	v_fmac_f32_e32 v213, v21, v157
	v_fmac_f32_e32 v210, v22, v158
	v_fmac_f32_e32 v211, v22, v159
	v_fmac_f32_e32 v212, v22, v160
	v_fmac_f32_e32 v213, v22, v161
	v_fmac_f32_e32 v210, v23, v162
	v_fmac_f32_e32 v211, v23, v163
	v_fmac_f32_e32 v212, v23, v164
	v_fmac_f32_e32 v213, v23, v165
	v_add_f32_dpp v210, v210, v210 row_ror:8 row_mask:0xf bank_mask:0xf
	v_add_f32_dpp v211, v211, v211 row_ror:8 row_mask:0xf bank_mask:0xf
	v_add_f32_dpp v212, v212, v212 row_ror:8 row_mask:0xf bank_mask:0xf
	v_add_f32_dpp v213, v213, v213 row_ror:8 row_mask:0xf bank_mask:0xf
	v_add_f32_dpp v210, v210, v210 row_ror:4 row_mask:0xf bank_mask:0xf
	v_add_f32_dpp v211, v211, v211 row_ror:4 row_mask:0xf bank_mask:0xf
	v_add_f32_dpp v212, v212, v212 row_ror:4 row_mask:0xf bank_mask:0xf
	v_add_f32_dpp v213, v213, v213 row_ror:4 row_mask:0xf bank_mask:0xf
	v_add_f32_dpp v210, v210, v210 row_ror:2 row_mask:0xf bank_mask:0xf
	v_add_f32_dpp v211, v211, v211 row_ror:2 row_mask:0xf bank_mask:0xf
	v_add_f32_dpp v212, v212, v212 row_ror:2 row_mask:0xf bank_mask:0xf
	v_add_f32_dpp v213, v213, v213 row_ror:2 row_mask:0xf bank_mask:0xf
	v_add_f32_dpp v210, v210, v210 row_ror:1 row_mask:0xf bank_mask:0xf
	v_add_f32_dpp v211, v211, v211 row_ror:1 row_mask:0xf bank_mask:0xf
	v_add_f32_dpp v212, v212, v212 row_ror:1 row_mask:0xf bank_mask:0xf
	v_add_f32_dpp v213, v213, v213 row_ror:1 row_mask:0xf bank_mask:0xf
	s_mov_b64 exec, s[2:3]
	ds_write_b128 v251, v[210:213] offset:320
	s_mov_b64 exec, -1
	s_waitcnt vmcnt(9)
; template <int L, int N> DEVQ void filt_item(const Params& P, LAS unsigned char* lds, const float* H3v, int d, cf* specd, float* cornerd) {
;     ...
;         for (int i4 = 0; i4 < 16; ++i4) hv[i4] = hr[i4];
; #pragma unroll
;         for (int i4 = 0; i4 < 16; ++i4) { if ((i4 & 3) == 0) asm volatile("" ::: "memory");
;             acc += hv[i4].x * wc4[4 * i4] + hv[i4].y * wc4[4 * i4 + 1] + hv[i4].z * wc4[4 * i4 + 2] + hv[i4].w * wc4[4 * i4 + 3]; }
	v_mul_f32_e32 v194, v24, v148
	v_mul_f32_e32 v195, v24, v149
	v_mul_f32_e32 v196, v24, v150
	v_mul_f32_e32 v197, v24, v151
	v_fmac_f32_e32 v194, v25, v154
	v_fmac_f32_e32 v195, v25, v155
	v_fmac_f32_e32 v196, v25, v156
	v_fmac_f32_e32 v197, v25, v157
	v_fmac_f32_e32 v194, v26, v158
	v_fmac_f32_e32 v195, v26, v159
	v_fmac_f32_e32 v196, v26, v160
	v_fmac_f32_e32 v197, v26, v161
	v_fmac_f32_e32 v194, v27, v162
	v_fmac_f32_e32 v195, v27, v163
	v_fmac_f32_e32 v196, v27, v164
	v_fmac_f32_e32 v197, v27, v165
	v_add_f32_dpp v194, v194, v194 row_ror:8 row_mask:0xf bank_mask:0xf
	v_add_f32_dpp v195, v195, v195 row_ror:8 row_mask:0xf bank_mask:0xf
	v_add_f32_dpp v196, v196, v196 row_ror:8 row_mask:0xf bank_mask:0xf
	v_add_f32_dpp v197, v197, v197 row_ror:8 row_mask:0xf bank_mask:0xf
	v_add_f32_dpp v194, v194, v194 row_ror:4 row_mask:0xf bank_mask:0xf
	v_add_f32_dpp v195, v195, v195 row_ror:4 row_mask:0xf bank_mask:0xf
	v_add_f32_dpp v196, v196, v196 row_ror:4 row_mask:0xf bank_mask:0xf
	v_add_f32_dpp v197, v197, v197 row_ror:4 row_mask:0xf bank_mask:0xf
	v_add_f32_dpp v194, v194, v194 row_ror:2 row_mask:0xf bank_mask:0xf
	v_add_f32_dpp v195, v195, v195 row_ror:2 row_mask:0xf bank_mask:0xf
	v_add_f32_dpp v196, v196, v196 row_ror:2 row_mask:0xf bank_mask:0xf
	v_add_f32_dpp v197, v197, v197 row_ror:2 row_mask:0xf bank_mask:0xf
	v_add_f32_dpp v194, v194, v194 row_ror:1 row_mask:0xf bank_mask:0xf
	v_add_f32_dpp v195, v195, v195 row_ror:1 row_mask:0xf bank_mask:0xf
	v_add_f32_dpp v196, v196, v196 row_ror:1 row_mask:0xf bank_mask:0xf
	v_add_f32_dpp v197, v197, v197 row_ror:1 row_mask:0xf bank_mask:0xf
	s_mov_b64 exec, s[2:3]
	ds_write_b128 v251, v[194:197] offset:384
	s_mov_b64 exec, -1
	s_waitcnt vmcnt(8)
	v_mul_f32_e32 v210, v28, v148
	v_mul_f32_e32 v211, v28, v149
	v_mul_f32_e32 v212, v28, v150
	v_mul_f32_e32 v213, v28, v151
	v_fmac_f32_e32 v210, v29, v154
	v_fmac_f32_e32 v211, v29, v155
	v_fmac_f32_e32 v212, v29, v156
	v_fmac_f32_e32 v213, v29, v157
	v_fmac_f32_e32 v210, v30, v158
	v_fmac_f32_e32 v211, v30, v159
	v_fmac_f32_e32 v212, v30, v160
	v_fmac_f32_e32 v213, v30, v161
	v_fmac_f32_e32 v210, v31, v162
	v_fmac_f32_e32 v211, v31, v163
	v_fmac_f32_e32 v212, v31, v164
	v_fmac_f32_e32 v213, v31, v165
	v_add_f32_dpp v210, v210, v210 row_ror:8 row_mask:0xf bank_mask:0xf
	v_add_f32_dpp v211, v211, v211 row_ror:8 row_mask:0xf bank_mask:0xf
	v_add_f32_dpp v212, v212, v212 row_ror:8 row_mask:0xf bank_mask:0xf
	v_add_f32_dpp v213, v213, v213 row_ror:8 row_mask:0xf bank_mask:0xf
	v_add_f32_dpp v210, v210, v210 row_ror:4 row_mask:0xf bank_mask:0xf
	v_add_f32_dpp v211, v211, v211 row_ror:4 row_mask:0xf bank_mask:0xf
	v_add_f32_dpp v212, v212, v212 row_ror:4 row_mask:0xf bank_mask:0xf
	v_add_f32_dpp v213, v213, v213 row_ror:4 row_mask:0xf bank_mask:0xf
	v_add_f32_dpp v210, v210, v210 row_ror:2 row_mask:0xf bank_mask:0xf
	v_add_f32_dpp v211, v211, v211 row_ror:2 row_mask:0xf bank_mask:0xf
	v_add_f32_dpp v212, v212, v212 row_ror:2 row_mask:0xf bank_mask:0xf
	v_add_f32_dpp v213, v213, v213 row_ror:2 row_mask:0xf bank_mask:0xf
	v_add_f32_dpp v210, v210, v210 row_ror:1 row_mask:0xf bank_mask:0xf
	v_add_f32_dpp v211, v211, v211 row_ror:1 row_mask:0xf bank_mask:0xf
	v_add_f32_dpp v212, v212, v212 row_ror:1 row_mask:0xf bank_mask:0xf
	v_add_f32_dpp v213, v213, v213 row_ror:1 row_mask:0xf bank_mask:0xf
	s_mov_b64 exec, s[2:3]
	ds_write_b128 v251, v[210:213] offset:448
	s_mov_b64 exec, -1
	s_waitcnt vmcnt(7)
	v_mul_f32_e32 v194, v32, v148
	v_mul_f32_e32 v195, v32, v149
	v_mul_f32_e32 v196, v32, v150
	v_mul_f32_e32 v197, v32, v151
	v_fmac_f32_e32 v194, v33, v154
	v_fmac_f32_e32 v195, v33, v155
	v_fmac_f32_e32 v196, v33, v156
	v_fmac_f32_e32 v197, v33, v157
	v_fmac_f32_e32 v194, v34, v158
	v_fmac_f32_e32 v195, v34, v159
	v_fmac_f32_e32 v196, v34, v160
	v_fmac_f32_e32 v197, v34, v161
	v_fmac_f32_e32 v194, v35, v162
	v_fmac_f32_e32 v195, v35, v163
	v_fmac_f32_e32 v196, v35, v164
	v_fmac_f32_e32 v197, v35, v165
	v_add_f32_dpp v194, v194, v194 row_ror:8 row_mask:0xf bank_mask:0xf
	v_add_f32_dpp v195, v195, v195 row_ror:8 row_mask:0xf bank_mask:0xf
	v_add_f32_dpp v196, v196, v196 row_ror:8 row_mask:0xf bank_mask:0xf
	v_add_f32_dpp v197, v197, v197 row_ror:8 row_mask:0xf bank_mask:0xf
	v_add_f32_dpp v194, v194, v194 row_ror:4 row_mask:0xf bank_mask:0xf
	v_add_f32_dpp v195, v195, v195 row_ror:4 row_mask:0xf bank_mask:0xf
	v_add_f32_dpp v196, v196, v196 row_ror:4 row_mask:0xf bank_mask:0xf
	v_add_f32_dpp v197, v197, v197 row_ror:4 row_mask:0xf bank_mask:0xf
	v_add_f32_dpp v194, v194, v194 row_ror:2 row_mask:0xf bank_mask:0xf
	v_add_f32_dpp v195, v195, v195 row_ror:2 row_mask:0xf bank_mask:0xf
	v_add_f32_dpp v196, v196, v196 row_ror:2 row_mask:0xf bank_mask:0xf
	v_add_f32_dpp v197, v197, v197 row_ror:2 row_mask:0xf bank_mask:0xf
	v_add_f32_dpp v194, v194, v194 row_ror:1 row_mask:0xf bank_mask:0xf
	v_add_f32_dpp v195, v195, v195 row_ror:1 row_mask:0xf bank_mask:0xf
	v_add_f32_dpp v196, v196, v196 row_ror:1 row_mask:0xf bank_mask:0xf
	v_add_f32_dpp v197, v197, v197 row_ror:1 row_mask:0xf bank_mask:0xf
	s_mov_b64 exec, s[2:3]
	ds_write_b128 v251, v[194:197] offset:512
	s_mov_b64 exec, -1
	s_waitcnt vmcnt(6)
; template <int L, int N> DEVQ void filt_item(const Params& P, LAS unsigned char* lds, const float* H3v, int d, cf* specd, float* cornerd) {
;     ...
;         for (int i4 = 0; i4 < 16; ++i4) hv[i4] = hr[i4];
; #pragma unroll
;         for (int i4 = 0; i4 < 16; ++i4) { if ((i4 & 3) == 0) asm volatile("" ::: "memory");
;             acc += hv[i4].x * wc4[4 * i4] + hv[i4].y * wc4[4 * i4 + 1] + hv[i4].z * wc4[4 * i4 + 2] + hv[i4].w * wc4[4 * i4 + 3]; }
	v_mul_f32_e32 v210, v36, v148
	v_mul_f32_e32 v211, v36, v149
	v_mul_f32_e32 v212, v36, v150
	v_mul_f32_e32 v213, v36, v151
	v_fmac_f32_e32 v210, v37, v154
	v_fmac_f32_e32 v211, v37, v155
	v_fmac_f32_e32 v212, v37, v156
	v_fmac_f32_e32 v213, v37, v157
	v_fmac_f32_e32 v210, v38, v158
	v_fmac_f32_e32 v211, v38, v159
	v_fmac_f32_e32 v212, v38, v160
	v_fmac_f32_e32 v213, v38, v161
	v_fmac_f32_e32 v210, v39, v162
	v_fmac_f32_e32 v211, v39, v163
	v_fmac_f32_e32 v212, v39, v164
	v_fmac_f32_e32 v213, v39, v165
	v_add_f32_dpp v210, v210, v210 row_ror:8 row_mask:0xf bank_mask:0xf
	v_add_f32_dpp v211, v211, v211 row_ror:8 row_mask:0xf bank_mask:0xf
	v_add_f32_dpp v212, v212, v212 row_ror:8 row_mask:0xf bank_mask:0xf
	v_add_f32_dpp v213, v213, v213 row_ror:8 row_mask:0xf bank_mask:0xf
	v_add_f32_dpp v210, v210, v210 row_ror:4 row_mask:0xf bank_mask:0xf
	v_add_f32_dpp v211, v211, v211 row_ror:4 row_mask:0xf bank_mask:0xf
	v_add_f32_dpp v212, v212, v212 row_ror:4 row_mask:0xf bank_mask:0xf
	v_add_f32_dpp v213, v213, v213 row_ror:4 row_mask:0xf bank_mask:0xf
	v_add_f32_dpp v210, v210, v210 row_ror:2 row_mask:0xf bank_mask:0xf
	v_add_f32_dpp v211, v211, v211 row_ror:2 row_mask:0xf bank_mask:0xf
	v_add_f32_dpp v212, v212, v212 row_ror:2 row_mask:0xf bank_mask:0xf
	v_add_f32_dpp v213, v213, v213 row_ror:2 row_mask:0xf bank_mask:0xf
	v_add_f32_dpp v210, v210, v210 row_ror:1 row_mask:0xf bank_mask:0xf
	v_add_f32_dpp v211, v211, v211 row_ror:1 row_mask:0xf bank_mask:0xf
	v_add_f32_dpp v212, v212, v212 row_ror:1 row_mask:0xf bank_mask:0xf
	v_add_f32_dpp v213, v213, v213 row_ror:1 row_mask:0xf bank_mask:0xf
	s_mov_b64 exec, s[2:3]
	ds_write_b128 v251, v[210:213] offset:576
	s_mov_b64 exec, -1
	s_waitcnt vmcnt(5)
	v_mul_f32_e32 v194, v40, v148
	v_mul_f32_e32 v195, v40, v149
	v_mul_f32_e32 v196, v40, v150
	v_mul_f32_e32 v197, v40, v151
	v_fmac_f32_e32 v194, v41, v154
	v_fmac_f32_e32 v195, v41, v155
	v_fmac_f32_e32 v196, v41, v156
	v_fmac_f32_e32 v197, v41, v157
	v_fmac_f32_e32 v194, v42, v158
	v_fmac_f32_e32 v195, v42, v159
	v_fmac_f32_e32 v196, v42, v160
	v_fmac_f32_e32 v197, v42, v161
	v_fmac_f32_e32 v194, v43, v162
	v_fmac_f32_e32 v195, v43, v163
	v_fmac_f32_e32 v196, v43, v164
	v_fmac_f32_e32 v197, v43, v165
	v_add_f32_dpp v194, v194, v194 row_ror:8 row_mask:0xf bank_mask:0xf
	v_add_f32_dpp v195, v195, v195 row_ror:8 row_mask:0xf bank_mask:0xf
	v_add_f32_dpp v196, v196, v196 row_ror:8 row_mask:0xf bank_mask:0xf
	v_add_f32_dpp v197, v197, v197 row_ror:8 row_mask:0xf bank_mask:0xf
	v_add_f32_dpp v194, v194, v194 row_ror:4 row_mask:0xf bank_mask:0xf
	v_add_f32_dpp v195, v195, v195 row_ror:4 row_mask:0xf bank_mask:0xf
	v_add_f32_dpp v196, v196, v196 row_ror:4 row_mask:0xf bank_mask:0xf
	v_add_f32_dpp v197, v197, v197 row_ror:4 row_mask:0xf bank_mask:0xf
	v_add_f32_dpp v194, v194, v194 row_ror:2 row_mask:0xf bank_mask:0xf
	v_add_f32_dpp v195, v195, v195 row_ror:2 row_mask:0xf bank_mask:0xf
	v_add_f32_dpp v196, v196, v196 row_ror:2 row_mask:0xf bank_mask:0xf
	v_add_f32_dpp v197, v197, v197 row_ror:2 row_mask:0xf bank_mask:0xf
	v_add_f32_dpp v194, v194, v194 row_ror:1 row_mask:0xf bank_mask:0xf
	v_add_f32_dpp v195, v195, v195 row_ror:1 row_mask:0xf bank_mask:0xf
	v_add_f32_dpp v196, v196, v196 row_ror:1 row_mask:0xf bank_mask:0xf
	v_add_f32_dpp v197, v197, v197 row_ror:1 row_mask:0xf bank_mask:0xf
	s_mov_b64 exec, s[2:3]
	ds_write_b128 v251, v[194:197] offset:640
	s_mov_b64 exec, -1
	s_waitcnt vmcnt(4)
	v_mul_f32_e32 v210, v44, v148
	v_mul_f32_e32 v211, v44, v149
	v_mul_f32_e32 v212, v44, v150
	v_mul_f32_e32 v213, v44, v151
	v_fmac_f32_e32 v210, v45, v154
	v_fmac_f32_e32 v211, v45, v155
	v_fmac_f32_e32 v212, v45, v156
	v_fmac_f32_e32 v213, v45, v157
	v_fmac_f32_e32 v210, v46, v158
	v_fmac_f32_e32 v211, v46, v159
	v_fmac_f32_e32 v212, v46, v160
	v_fmac_f32_e32 v213, v46, v161
	v_fmac_f32_e32 v210, v47, v162
	v_fmac_f32_e32 v211, v47, v163
	v_fmac_f32_e32 v212, v47, v164
	v_fmac_f32_e32 v213, v47, v165
	v_add_f32_dpp v210, v210, v210 row_ror:8 row_mask:0xf bank_mask:0xf
	v_add_f32_dpp v211, v211, v211 row_ror:8 row_mask:0xf bank_mask:0xf
	v_add_f32_dpp v212, v212, v212 row_ror:8 row_mask:0xf bank_mask:0xf
	v_add_f32_dpp v213, v213, v213 row_ror:8 row_mask:0xf bank_mask:0xf
	v_add_f32_dpp v210, v210, v210 row_ror:4 row_mask:0xf bank_mask:0xf
	v_add_f32_dpp v211, v211, v211 row_ror:4 row_mask:0xf bank_mask:0xf
	v_add_f32_dpp v212, v212, v212 row_ror:4 row_mask:0xf bank_mask:0xf
	v_add_f32_dpp v213, v213, v213 row_ror:4 row_mask:0xf bank_mask:0xf
	v_add_f32_dpp v210, v210, v210 row_ror:2 row_mask:0xf bank_mask:0xf
	v_add_f32_dpp v211, v211, v211 row_ror:2 row_mask:0xf bank_mask:0xf
	v_add_f32_dpp v212, v212, v212 row_ror:2 row_mask:0xf bank_mask:0xf
	v_add_f32_dpp v213, v213, v213 row_ror:2 row_mask:0xf bank_mask:0xf
	v_add_f32_dpp v210, v210, v210 row_ror:1 row_mask:0xf bank_mask:0xf
	v_add_f32_dpp v211, v211, v211 row_ror:1 row_mask:0xf bank_mask:0xf
	v_add_f32_dpp v212, v212, v212 row_ror:1 row_mask:0xf bank_mask:0xf
	v_add_f32_dpp v213, v213, v213 row_ror:1 row_mask:0xf bank_mask:0xf
	s_mov_b64 exec, s[2:3]
	ds_write_b128 v251, v[210:213] offset:704
	s_mov_b64 exec, -1
	s_waitcnt vmcnt(3)
; template <int L, int N> DEVQ void filt_item(const Params& P, LAS unsigned char* lds, const float* H3v, int d, cf* specd, float* cornerd) {
;     ...
;         for (int i4 = 0; i4 < 16; ++i4) hv[i4] = hr[i4];
; #pragma unroll
;         for (int i4 = 0; i4 < 16; ++i4) { if ((i4 & 3) == 0) asm volatile("" ::: "memory");
;             acc += hv[i4].x * wc4[4 * i4] + hv[i4].y * wc4[4 * i4 + 1] + hv[i4].z * wc4[4 * i4 + 2] + hv[i4].w * wc4[4 * i4 + 3]; }
	v_mul_f32_e32 v194, v48, v148
	v_mul_f32_e32 v195, v48, v149
	v_mul_f32_e32 v196, v48, v150
	v_mul_f32_e32 v197, v48, v151
	v_fmac_f32_e32 v194, v49, v154
	v_fmac_f32_e32 v195, v49, v155
	v_fmac_f32_e32 v196, v49, v156
	v_fmac_f32_e32 v197, v49, v157
	v_fmac_f32_e32 v194, v50, v158
	v_fmac_f32_e32 v195, v50, v159
	v_fmac_f32_e32 v196, v50, v160
	v_fmac_f32_e32 v197, v50, v161
	v_fmac_f32_e32 v194, v51, v162
	v_fmac_f32_e32 v195, v51, v163
	v_fmac_f32_e32 v196, v51, v164
	v_fmac_f32_e32 v197, v51, v165
	v_add_f32_dpp v194, v194, v194 row_ror:8 row_mask:0xf bank_mask:0xf
	v_add_f32_dpp v195, v195, v195 row_ror:8 row_mask:0xf bank_mask:0xf
	v_add_f32_dpp v196, v196, v196 row_ror:8 row_mask:0xf bank_mask:0xf
	v_add_f32_dpp v197, v197, v197 row_ror:8 row_mask:0xf bank_mask:0xf
	v_add_f32_dpp v194, v194, v194 row_ror:4 row_mask:0xf bank_mask:0xf
	v_add_f32_dpp v195, v195, v195 row_ror:4 row_mask:0xf bank_mask:0xf
	v_add_f32_dpp v196, v196, v196 row_ror:4 row_mask:0xf bank_mask:0xf
	v_add_f32_dpp v197, v197, v197 row_ror:4 row_mask:0xf bank_mask:0xf
	v_add_f32_dpp v194, v194, v194 row_ror:2 row_mask:0xf bank_mask:0xf
	v_add_f32_dpp v195, v195, v195 row_ror:2 row_mask:0xf bank_mask:0xf
	v_add_f32_dpp v196, v196, v196 row_ror:2 row_mask:0xf bank_mask:0xf
	v_add_f32_dpp v197, v197, v197 row_ror:2 row_mask:0xf bank_mask:0xf
	v_add_f32_dpp v194, v194, v194 row_ror:1 row_mask:0xf bank_mask:0xf
	v_add_f32_dpp v195, v195, v195 row_ror:1 row_mask:0xf bank_mask:0xf
	v_add_f32_dpp v196, v196, v196 row_ror:1 row_mask:0xf bank_mask:0xf
	v_add_f32_dpp v197, v197, v197 row_ror:1 row_mask:0xf bank_mask:0xf
	s_mov_b64 exec, s[2:3]
	ds_write_b128 v251, v[194:197] offset:768
	s_mov_b64 exec, -1
	s_waitcnt vmcnt(2)
	v_mul_f32_e32 v210, v52, v148
	v_mul_f32_e32 v211, v52, v149
	v_mul_f32_e32 v212, v52, v150
	v_mul_f32_e32 v213, v52, v151
	v_fmac_f32_e32 v210, v53, v154
	v_fmac_f32_e32 v211, v53, v155
	v_fmac_f32_e32 v212, v53, v156
	v_fmac_f32_e32 v213, v53, v157
	v_fmac_f32_e32 v210, v54, v158
	v_fmac_f32_e32 v211, v54, v159
	v_fmac_f32_e32 v212, v54, v160
	v_fmac_f32_e32 v213, v54, v161
	v_fmac_f32_e32 v210, v55, v162
	v_fmac_f32_e32 v211, v55, v163
	v_fmac_f32_e32 v212, v55, v164
	v_fmac_f32_e32 v213, v55, v165
	v_add_f32_dpp v210, v210, v210 row_ror:8 row_mask:0xf bank_mask:0xf
	v_add_f32_dpp v211, v211, v211 row_ror:8 row_mask:0xf bank_mask:0xf
	v_add_f32_dpp v212, v212, v212 row_ror:8 row_mask:0xf bank_mask:0xf
	v_add_f32_dpp v213, v213, v213 row_ror:8 row_mask:0xf bank_mask:0xf
	v_add_f32_dpp v210, v210, v210 row_ror:4 row_mask:0xf bank_mask:0xf
	v_add_f32_dpp v211, v211, v211 row_ror:4 row_mask:0xf bank_mask:0xf
	v_add_f32_dpp v212, v212, v212 row_ror:4 row_mask:0xf bank_mask:0xf
	v_add_f32_dpp v213, v213, v213 row_ror:4 row_mask:0xf bank_mask:0xf
	v_add_f32_dpp v210, v210, v210 row_ror:2 row_mask:0xf bank_mask:0xf
	v_add_f32_dpp v211, v211, v211 row_ror:2 row_mask:0xf bank_mask:0xf
	v_add_f32_dpp v212, v212, v212 row_ror:2 row_mask:0xf bank_mask:0xf
	v_add_f32_dpp v213, v213, v213 row_ror:2 row_mask:0xf bank_mask:0xf
	v_add_f32_dpp v210, v210, v210 row_ror:1 row_mask:0xf bank_mask:0xf
	v_add_f32_dpp v211, v211, v211 row_ror:1 row_mask:0xf bank_mask:0xf
	v_add_f32_dpp v212, v212, v212 row_ror:1 row_mask:0xf bank_mask:0xf
	v_add_f32_dpp v213, v213, v213 row_ror:1 row_mask:0xf bank_mask:0xf
	s_mov_b64 exec, s[2:3]
	ds_write_b128 v251, v[210:213] offset:832
	s_mov_b64 exec, -1
	s_waitcnt vmcnt(1)
; template <int L, int N> DEVQ void filt_item(const Params& P, LAS unsigned char* lds, const float* H3v, int d, cf* specd, float* cornerd) {
;     ...
;         for (int i4 = 0; i4 < 16; ++i4) hv[i4] = hr[i4];
; #pragma unroll
;         for (int i4 = 0; i4 < 16; ++i4) { if ((i4 & 3) == 0) asm volatile("" ::: "memory");
;             acc += hv[i4].x * wc4[4 * i4] + hv[i4].y * wc4[4 * i4 + 1] + hv[i4].z * wc4[4 * i4 + 2] + hv[i4].w * wc4[4 * i4 + 3]; }
;         const float dec = expf(-((float)k / (float)(L - 1)) * delta);
;         acc *= dec;
;         if (k <= N / 2) X[swz(k)] = cf{acc.x * invN, acc.z * invN};
	v_mul_f32_e32 v194, v56, v148
	v_mul_f32_e32 v195, v56, v149
	v_mul_f32_e32 v196, v56, v150
	v_mul_f32_e32 v197, v56, v151
	v_fmac_f32_e32 v194, v57, v154
	v_fmac_f32_e32 v195, v57, v155
	v_fmac_f32_e32 v196, v57, v156
	v_fmac_f32_e32 v197, v57, v157
	v_fmac_f32_e32 v194, v58, v158
	v_fmac_f32_e32 v195, v58, v159
	v_fmac_f32_e32 v196, v58, v160
	v_fmac_f32_e32 v197, v58, v161
	v_fmac_f32_e32 v194, v59, v162
	v_fmac_f32_e32 v195, v59, v163
	v_fmac_f32_e32 v196, v59, v164
	v_fmac_f32_e32 v197, v59, v165
	v_add_f32_dpp v194, v194, v194 row_ror:8 row_mask:0xf bank_mask:0xf
	v_add_f32_dpp v195, v195, v195 row_ror:8 row_mask:0xf bank_mask:0xf
	v_add_f32_dpp v196, v196, v196 row_ror:8 row_mask:0xf bank_mask:0xf
	v_add_f32_dpp v197, v197, v197 row_ror:8 row_mask:0xf bank_mask:0xf
	v_add_f32_dpp v194, v194, v194 row_ror:4 row_mask:0xf bank_mask:0xf
	v_add_f32_dpp v195, v195, v195 row_ror:4 row_mask:0xf bank_mask:0xf
	v_add_f32_dpp v196, v196, v196 row_ror:4 row_mask:0xf bank_mask:0xf
	v_add_f32_dpp v197, v197, v197 row_ror:4 row_mask:0xf bank_mask:0xf
	v_add_f32_dpp v194, v194, v194 row_ror:2 row_mask:0xf bank_mask:0xf
	v_add_f32_dpp v195, v195, v195 row_ror:2 row_mask:0xf bank_mask:0xf
	v_add_f32_dpp v196, v196, v196 row_ror:2 row_mask:0xf bank_mask:0xf
	v_add_f32_dpp v197, v197, v197 row_ror:2 row_mask:0xf bank_mask:0xf
	v_add_f32_dpp v194, v194, v194 row_ror:1 row_mask:0xf bank_mask:0xf
	v_add_f32_dpp v195, v195, v195 row_ror:1 row_mask:0xf bank_mask:0xf
	v_add_f32_dpp v196, v196, v196 row_ror:1 row_mask:0xf bank_mask:0xf
	v_add_f32_dpp v197, v197, v197 row_ror:1 row_mask:0xf bank_mask:0xf
	s_mov_b64 exec, s[2:3]
	ds_write_b128 v251, v[194:197] offset:896
	s_mov_b64 exec, -1
	s_waitcnt vmcnt(0)
	v_mul_f32_e32 v210, v60, v148
	v_mul_f32_e32 v211, v60, v149
	v_mul_f32_e32 v212, v60, v150
	v_mul_f32_e32 v213, v60, v151
	v_fmac_f32_e32 v210, v61, v154
	v_fmac_f32_e32 v211, v61, v155
	v_fmac_f32_e32 v212, v61, v156
	v_fmac_f32_e32 v213, v61, v157
	v_fmac_f32_e32 v210, v62, v158
	v_fmac_f32_e32 v211, v62, v159
	v_fmac_f32_e32 v212, v62, v160
	v_fmac_f32_e32 v213, v62, v161
	v_fmac_f32_e32 v210, v63, v162
	v_fmac_f32_e32 v211, v63, v163
	v_fmac_f32_e32 v212, v63, v164
	v_fmac_f32_e32 v213, v63, v165
	v_add_f32_dpp v210, v210, v210 row_ror:8 row_mask:0xf bank_mask:0xf
	v_add_f32_dpp v211, v211, v211 row_ror:8 row_mask:0xf bank_mask:0xf
	v_add_f32_dpp v212, v212, v212 row_ror:8 row_mask:0xf bank_mask:0xf
	v_add_f32_dpp v213, v213, v213 row_ror:8 row_mask:0xf bank_mask:0xf
	v_add_f32_dpp v210, v210, v210 row_ror:4 row_mask:0xf bank_mask:0xf
	v_add_f32_dpp v211, v211, v211 row_ror:4 row_mask:0xf bank_mask:0xf
	v_add_f32_dpp v212, v212, v212 row_ror:4 row_mask:0xf bank_mask:0xf
	v_add_f32_dpp v213, v213, v213 row_ror:4 row_mask:0xf bank_mask:0xf
	v_add_f32_dpp v210, v210, v210 row_ror:2 row_mask:0xf bank_mask:0xf
	v_add_f32_dpp v211, v211, v211 row_ror:2 row_mask:0xf bank_mask:0xf
	v_add_f32_dpp v212, v212, v212 row_ror:2 row_mask:0xf bank_mask:0xf
	v_add_f32_dpp v213, v213, v213 row_ror:2 row_mask:0xf bank_mask:0xf
	v_add_f32_dpp v210, v210, v210 row_ror:1 row_mask:0xf bank_mask:0xf
	v_add_f32_dpp v211, v211, v211 row_ror:1 row_mask:0xf bank_mask:0xf
	v_add_f32_dpp v212, v212, v212 row_ror:1 row_mask:0xf bank_mask:0xf
	v_add_f32_dpp v213, v213, v213 row_ror:1 row_mask:0xf bank_mask:0xf
	s_mov_b64 exec, s[2:3]
	ds_write_b128 v251, v[210:213] offset:960
	s_mov_b64 exec, -1
	s_waitcnt lgkmcnt(0)
	ds_read_b128 v[0:3], v250
	s_mov_b32 s11, 0xc5807800
	v_cvt_f32_i32_e32 v4, v75
	s_waitcnt lgkmcnt(0)
	s_mov_b64 exec, s[14:15]
	v_div_scale_f32 v5, s[2:3], s11, s11, v4
	v_rcp_f32_e32 v6, v5
	s_mov_b32 s2, 0xc2ce8ed0
	v_fma_f32 v7, -v5, v6, 1.0
	v_fmac_f32_e32 v6, v7, v6
	v_div_scale_f32 v7, vcc, v4, s11, v4
	v_mul_f32_e32 v8, v7, v6
	v_fma_f32 v9, -v5, v8, v7
	v_fmac_f32_e32 v8, v9, v6
	v_fma_f32 v5, -v5, v8, v7
	v_div_fmas_f32 v5, v5, v6, v8
	v_div_fixup_f32 v4, v5, s11, v4
	v_mul_f32_e64 v4, |v74|, v4
	v_mul_f32_e32 v5, 0x3fb8aa3b, v4
	v_fma_f32 v6, v4, s18, -v5
	v_rndne_f32_e32 v7, v5
	v_fmac_f32_e32 v6, 0x32a5705f, v4
	v_sub_f32_e32 v5, v5, v7
	v_add_f32_e32 v5, v5, v6
	v_exp_f32_e32 v5, v5
	v_cvt_i32_f32_e32 v6, v7
	v_cmp_ngt_f32_e32 vcc, s2, v4
	s_mov_b32 s2, 0x42b17218
	v_ldexp_f32 v5, v5, v6
	v_cndmask_b32_e32 v5, 0, v5, vcc
	v_cmp_nlt_f32_e32 vcc, s2, v4
	s_movk_i32 s2, 0x1001
	s_nop 0
	v_cndmask_b32_e32 v4, v188, v5, vcc
	v_pk_mul_f32 v[0:1], v[4:5], v[0:1] op_sel_hi:[0,1]
	v_pk_mul_f32 v[2:3], v[4:5], v[2:3] op_sel_hi:[0,1]
	v_cmp_gt_i32_e32 vcc, s2, v75
	s_and_saveexec_b64 s[14:15], vcc
	s_cbranch_execz .LBB0_593
	v_ashrrev_i32_e32 v6, 5, v75
	v_lshlrev_b32_e32 v7, 2, v6
	v_and_b32_e32 v7, 28, v7
	v_and_b32_e32 v6, 3, v6
	v_mov_b32_e32 v4, v0
	v_mov_b32_e32 v5, v2
	s_mov_b32 s2, 0x39000000
	v_bitop3_b32 v6, v7, v75, v6 bitop3:0x36
	v_pk_mul_f32 v[4:5], v[4:5], s[2:3] op_sel_hi:[1,0]
	v_lshl_add_u32 v6, v6, 3, 0
	ds_write_b64 v6, v[4:5]

; template <int L, int N> DEVQ void filt_item(const Params& P, LAS unsigned char* lds, const float* H3v, int d, cf* specd, float* cornerd) {
;     ...
;     const float delta = fabsf(MIN_DECAY + (float)d * ((MAX_DECAY - MIN_DECAY) / 1023.0f));
;     const float invN = 1.0f / (float)N;
;     for (int k = tid; k < L; k += NTHR) {
;         asm volatile("" ::: "memory");
;         const f32x4* hr = (const f32x4*)(H3v + (size_t)k * 64);
;         f32x4 acc = (f32x4){0.f, 0.f, 0.f, 0.f};
;         f32x4 hv[16];
; #pragma unroll
;         for (int i4 = 0; i4 < 16; ++i4) hv[i4] = hr[i4];
; #pragma unroll
;         for (int i4 = 0; i4 < 16; ++i4) { if ((i4 & 3) == 0) asm volatile("" ::: "memory");
;             acc += hv[i4].x * wc4[4 * i4] + hv[i4].y * wc4[4 * i4 + 1] + hv[i4].z * wc4[4 * i4 + 2] + hv[i4].w * wc4[4 * i4 + 3]; }
.LBB0_624:
	s_or_b64 exec, exec, s[0:1]
	s_movk_i32 s0, 0x2010
	v_cmp_gt_i32_e32 vcc, s0, v64
	s_waitcnt lgkmcnt(0)
	s_barrier
	s_and_saveexec_b64 s[0:1], vcc
	s_cbranch_execz .LBB0_633
	s_waitcnt vmcnt(0)
	v_cvt_f32_i32_e32 v2, s12
	v_readlane_b32 s2, v254, 32
	v_lshlrev_b64 v[0:1], 8, v[64:65]
	v_mov_b32_e32 v3, 0xc0447cbd
	v_lshl_add_u32 v72, v64, 2, s2
	v_sub_u32_e32 v73, 0x4000, v64
	v_fmamk_f32 v74, v2, 0xbc44ade8, v3
	v_lshl_add_u64 v[66:67], s[6:7], 0, v[0:1]
	s_mov_b64 s[14:15], 0
	v_mov_b32_e32 v75, v64
	v_mbcnt_lo_u32_b32 v202, -1, 0
	v_mbcnt_hi_u32_b32 v202, -1, v202
	v_mul_u32_u24_e32 v203, 0xf0, v202
	v_sub_u32_e32 v248, 0x1000, v203
	v_sub_u32_e32 v246, 0x3000, v203
	v_ashrrev_i32_e32 v249, 31, v248
	v_ashrrev_i32_e32 v247, 31, v246
	v_and_b32_e32 v203, 15, v202
	v_lshl_add_u32 v203, v203, 6, 0
	v_add_u32_e32 v203, 0x20000, v203
	ds_read_b128 v[148:151], v203
	ds_read_b128 v[154:157], v203 offset:16
	ds_read_b128 v[158:161], v203 offset:32
	ds_read_b128 v[162:165], v203 offset:48
	v_lshrrev_b32_e32 v204, 6, v64
	v_cmp_lt_u32_e64 s[2:3], 5, v204
	v_lshl_add_u32 v204, v204, 10, 0
	v_mov_b32_e32 v205, 0x400
	v_add_u32_e32 v204, 0x20800, v204
	v_cndmask_b32_e64 v205, 0, v205, s[2:3]
	v_add_u32_e32 v204, v204, v205
	v_lshrrev_b32_e32 v205, 4, v202
	v_lshl_add_u32 v251, v205, 4, v204
	v_lshl_add_u32 v250, v202, 4, v204
	s_waitcnt lgkmcnt(0)
	s_branch .LBB0_627

; template <int L, int N> DEVQ void filt_item(const Params& P, LAS unsigned char* lds, const float* H3v, int d, cf* specd, float* cornerd) {
;     ...
;         const f32x4* hr = (const f32x4*)(H3v + (size_t)k * 64);
;         f32x4 acc = (f32x4){0.f, 0.f, 0.f, 0.f};
;         f32x4 hv[16];
; #pragma unroll
;         for (int i4 = 0; i4 < 16; ++i4) hv[i4] = hr[i4];
; #pragma unroll
;         for (int i4 = 0; i4 < 16; ++i4) { if ((i4 & 3) == 0) asm volatile("" ::: "memory");
;             acc += hv[i4].x * wc4[4 * i4] + hv[i4].y * wc4[4 * i4 + 1] + hv[i4].z * wc4[4 * i4 + 2] + hv[i4].w * wc4[4 * i4 + 3]; }
.LBB0_627:
	s_mov_b64 s[20:21], exec
	s_mov_b64 exec, -1
	v_lshl_add_u64 v[198:199], v[66:67], 0, v[248:249]
	v_lshl_add_u64 v[200:201], v[66:67], 0, v[246:247]
	global_load_dwordx4 v[0:3], v[198:199], off offset:-4096
	global_load_dwordx4 v[4:7], v[198:199], off offset:-3072
	global_load_dwordx4 v[8:11], v[198:199], off offset:-2048
	global_load_dwordx4 v[12:15], v[198:199], off offset:-1024
	global_load_dwordx4 v[16:19], v[198:199], off offset:0
	global_load_dwordx4 v[20:23], v[198:199], off offset:1024
	global_load_dwordx4 v[24:27], v[198:199], off offset:2048
	global_load_dwordx4 v[28:31], v[198:199], off offset:3072
	global_load_dwordx4 v[32:35], v[200:201], off offset:-4096
	global_load_dwordx4 v[36:39], v[200:201], off offset:-3072
	global_load_dwordx4 v[40:43], v[200:201], off offset:-2048
	global_load_dwordx4 v[44:47], v[200:201], off offset:-1024
	global_load_dwordx4 v[48:51], v[200:201], off offset:0
	global_load_dwordx4 v[52:55], v[200:201], off offset:1024
	global_load_dwordx4 v[56:59], v[200:201], off offset:2048
	global_load_dwordx4 v[60:63], v[200:201], off offset:3072
	s_mov_b32 s2, 0x10001
	s_mov_b32 s3, 0x10001
	s_waitcnt vmcnt(15)
	v_mul_f32_e32 v194, v0, v148
	v_mul_f32_e32 v195, v0, v149
	v_mul_f32_e32 v196, v0, v150
	v_mul_f32_e32 v197, v0, v151
	v_fmac_f32_e32 v194, v1, v154
	v_fmac_f32_e32 v195, v1, v155
	v_fmac_f32_e32 v196, v1, v156
	v_fmac_f32_e32 v197, v1, v157
	v_fmac_f32_e32 v194, v2, v158
	v_fmac_f32_e32 v195, v2, v159
	v_fmac_f32_e32 v196, v2, v160
	v_fmac_f32_e32 v197, v2, v161
	v_fmac_f32_e32 v194, v3, v162
	v_fmac_f32_e32 v195, v3, v163
	v_fmac_f32_e32 v196, v3, v164
	v_fmac_f32_e32 v197, v3, v165
	v_add_f32_dpp v194, v194, v194 row_ror:8 row_mask:0xf bank_mask:0xf
	v_add_f32_dpp v195, v195, v195 row_ror:8 row_mask:0xf bank_mask:0xf
	v_add_f32_dpp v196, v196, v196 row_ror:8 row_mask:0xf bank_mask:0xf
	v_add_f32_dpp v197, v197, v197 row_ror:8 row_mask:0xf bank_mask:0xf
	v_add_f32_dpp v194, v194, v194 row_ror:4 row_mask:0xf bank_mask:0xf
	v_add_f32_dpp v195, v195, v195 row_ror:4 row_mask:0xf bank_mask:0xf
	v_add_f32_dpp v196, v196, v196 row_ror:4 row_mask:0xf bank_mask:0xf
	v_add_f32_dpp v197, v197, v197 row_ror:4 row_mask:0xf bank_mask:0xf
	v_add_f32_dpp v194, v194, v194 row_ror:2 row_mask:0xf bank_mask:0xf
	v_add_f32_dpp v195, v195, v195 row_ror:2 row_mask:0xf bank_mask:0xf
	v_add_f32_dpp v196, v196, v196 row_ror:2 row_mask:0xf bank_mask:0xf
	v_add_f32_dpp v197, v197, v197 row_ror:2 row_mask:0xf bank_mask:0xf
	v_add_f32_dpp v194, v194, v194 row_ror:1 row_mask:0xf bank_mask:0xf
	v_add_f32_dpp v195, v195, v195 row_ror:1 row_mask:0xf bank_mask:0xf
	v_add_f32_dpp v196, v196, v196 row_ror:1 row_mask:0xf bank_mask:0xf
	v_add_f32_dpp v197, v197, v197 row_ror:1 row_mask:0xf bank_mask:0xf
	s_mov_b64 exec, s[2:3]
	ds_write_b128 v251, v[194:197]
	s_mov_b64 exec, -1
	s_waitcnt vmcnt(14)
	v_mul_f32_e32 v210, v4, v148
	v_mul_f32_e32 v211, v4, v149
	v_mul_f32_e32 v212, v4, v150
	v_mul_f32_e32 v213, v4, v151
	v_fmac_f32_e32 v210, v5, v154
	v_fmac_f32_e32 v211, v5, v155
	v_fmac_f32_e32 v212, v5, v156
	v_fmac_f32_e32 v213, v5, v157
	v_fmac_f32_e32 v210, v6, v158
	v_fmac_f32_e32 v211, v6, v159
	v_fmac_f32_e32 v212, v6, v160
	v_fmac_f32_e32 v213, v6, v161
	v_fmac_f32_e32 v210, v7, v162
	v_fmac_f32_e32 v211, v7, v163
	v_fmac_f32_e32 v212, v7, v164
	v_fmac_f32_e32 v213, v7, v165
	v_add_f32_dpp v210, v210, v210 row_ror:8 row_mask:0xf bank_mask:0xf
	v_add_f32_dpp v211, v211, v211 row_ror:8 row_mask:0xf bank_mask:0xf
	v_add_f32_dpp v212, v212, v212 row_ror:8 row_mask:0xf bank_mask:0xf
	v_add_f32_dpp v213, v213, v213 row_ror:8 row_mask:0xf bank_mask:0xf
	v_add_f32_dpp v210, v210, v210 row_ror:4 row_mask:0xf bank_mask:0xf
	v_add_f32_dpp v211, v211, v211 row_ror:4 row_mask:0xf bank_mask:0xf
	v_add_f32_dpp v212, v212, v212 row_ror:4 row_mask:0xf bank_mask:0xf
	v_add_f32_dpp v213, v213, v213 row_ror:4 row_mask:0xf bank_mask:0xf
	v_add_f32_dpp v210, v210, v210 row_ror:2 row_mask:0xf bank_mask:0xf
	v_add_f32_dpp v211, v211, v211 row_ror:2 row_mask:0xf bank_mask:0xf
	v_add_f32_dpp v212, v212, v212 row_ror:2 row_mask:0xf bank_mask:0xf
	v_add_f32_dpp v213, v213, v213 row_ror:2 row_mask:0xf bank_mask:0xf
	v_add_f32_dpp v210, v210, v210 row_ror:1 row_mask:0xf bank_mask:0xf
	v_add_f32_dpp v211, v211, v211 row_ror:1 row_mask:0xf bank_mask:0xf
	v_add_f32_dpp v212, v212, v212 row_ror:1 row_mask:0xf bank_mask:0xf
	v_add_f32_dpp v213, v213, v213 row_ror:1 row_mask:0xf bank_mask:0xf
	s_mov_b64 exec, s[2:3]
	ds_write_b128 v251, v[210:213] offset:64
	s_mov_b64 exec, -1
	s_waitcnt vmcnt(13)
	v_mul_f32_e32 v194, v8, v148
	v_mul_f32_e32 v195, v8, v149
	v_mul_f32_e32 v196, v8, v150
	v_mul_f32_e32 v197, v8, v151
	v_fmac_f32_e32 v194, v9, v154
	v_fmac_f32_e32 v195, v9, v155
	v_fmac_f32_e32 v196, v9, v156
	v_fmac_f32_e32 v197, v9, v157
	v_fmac_f32_e32 v194, v10, v158
	v_fmac_f32_e32 v195, v10, v159
	v_fmac_f32_e32 v196, v10, v160
	v_fmac_f32_e32 v197, v10, v161
	v_fmac_f32_e32 v194, v11, v162
	v_fmac_f32_e32 v195, v11, v163
	v_fmac_f32_e32 v196, v11, v164
	v_fmac_f32_e32 v197, v11, v165
	v_add_f32_dpp v194, v194, v194 row_ror:8 row_mask:0xf bank_mask:0xf
	v_add_f32_dpp v195, v195, v195 row_ror:8 row_mask:0xf bank_mask:0xf
	v_add_f32_dpp v196, v196, v196 row_ror:8 row_mask:0xf bank_mask:0xf
	v_add_f32_dpp v197, v197, v197 row_ror:8 row_mask:0xf bank_mask:0xf
	v_add_f32_dpp v194, v194, v194 row_ror:4 row_mask:0xf bank_mask:0xf
	v_add_f32_dpp v195, v195, v195 row_ror:4 row_mask:0xf bank_mask:0xf
	v_add_f32_dpp v196, v196, v196 row_ror:4 row_mask:0xf bank_mask:0xf
	v_add_f32_dpp v197, v197, v197 row_ror:4 row_mask:0xf bank_mask:0xf
	v_add_f32_dpp v194, v194, v194 row_ror:2 row_mask:0xf bank_mask:0xf
	v_add_f32_dpp v195, v195, v195 row_ror:2 row_mask:0xf bank_mask:0xf
	v_add_f32_dpp v196, v196, v196 row_ror:2 row_mask:0xf bank_mask:0xf
	v_add_f32_dpp v197, v197, v197 row_ror:2 row_mask:0xf bank_mask:0xf
	v_add_f32_dpp v194, v194, v194 row_ror:1 row_mask:0xf bank_mask:0xf
	v_add_f32_dpp v195, v195, v195 row_ror:1 row_mask:0xf bank_mask:0xf
	v_add_f32_dpp v196, v196, v196 row_ror:1 row_mask:0xf bank_mask:0xf
	v_add_f32_dpp v197, v197, v197 row_ror:1 row_mask:0xf bank_mask:0xf
	s_mov_b64 exec, s[2:3]
	ds_write_b128 v251, v[194:197] offset:128
	s_mov_b64 exec, -1
	s_waitcnt vmcnt(12)
; template <int L, int N> DEVQ void filt_item(const Params& P, LAS unsigned char* lds, const float* H3v, int d, cf* specd, float* cornerd) {
;     ...
;         for (int i4 = 0; i4 < 16; ++i4) hv[i4] = hr[i4];
; #pragma unroll
;         for (int i4 = 0; i4 < 16; ++i4) { if ((i4 & 3) == 0) asm volatile("" ::: "memory");
;             acc += hv[i4].x * wc4[4 * i4] + hv[i4].y * wc4[4 * i4 + 1] + hv[i4].z * wc4[4 * i4 + 2] + hv[i4].w * wc4[4 * i4 + 3]; }
	v_mul_f32_e32 v210, v12, v148
	v_mul_f32_e32 v211, v12, v149
	v_mul_f32_e32 v212, v12, v150
	v_mul_f32_e32 v213, v12, v151
	v_fmac_f32_e32 v210, v13, v154
	v_fmac_f32_e32 v211, v13, v155
	v_fmac_f32_e32 v212, v13, v156
	v_fmac_f32_e32 v213, v13, v157
	v_fmac_f32_e32 v210, v14, v158
	v_fmac_f32_e32 v211, v14, v159
	v_fmac_f32_e32 v212, v14, v160
	v_fmac_f32_e32 v213, v14, v161
	v_fmac_f32_e32 v210, v15, v162
	v_fmac_f32_e32 v211, v15, v163
	v_fmac_f32_e32 v212, v15, v164
	v_fmac_f32_e32 v213, v15, v165
	v_add_f32_dpp v210, v210, v210 row_ror:8 row_mask:0xf bank_mask:0xf
	v_add_f32_dpp v211, v211, v211 row_ror:8 row_mask:0xf bank_mask:0xf
	v_add_f32_dpp v212, v212, v212 row_ror:8 row_mask:0xf bank_mask:0xf
	v_add_f32_dpp v213, v213, v213 row_ror:8 row_mask:0xf bank_mask:0xf
	v_add_f32_dpp v210, v210, v210 row_ror:4 row_mask:0xf bank_mask:0xf
	v_add_f32_dpp v211, v211, v211 row_ror:4 row_mask:0xf bank_mask:0xf
	v_add_f32_dpp v212, v212, v212 row_ror:4 row_mask:0xf bank_mask:0xf
	v_add_f32_dpp v213, v213, v213 row_ror:4 row_mask:0xf bank_mask:0xf
	v_add_f32_dpp v210, v210, v210 row_ror:2 row_mask:0xf bank_mask:0xf
	v_add_f32_dpp v211, v211, v211 row_ror:2 row_mask:0xf bank_mask:0xf
	v_add_f32_dpp v212, v212, v212 row_ror:2 row_mask:0xf bank_mask:0xf
	v_add_f32_dpp v213, v213, v213 row_ror:2 row_mask:0xf bank_mask:0xf
	v_add_f32_dpp v210, v210, v210 row_ror:1 row_mask:0xf bank_mask:0xf
	v_add_f32_dpp v211, v211, v211 row_ror:1 row_mask:0xf bank_mask:0xf
	v_add_f32_dpp v212, v212, v212 row_ror:1 row_mask:0xf bank_mask:0xf
	v_add_f32_dpp v213, v213, v213 row_ror:1 row_mask:0xf bank_mask:0xf
	s_mov_b64 exec, s[2:3]
	ds_write_b128 v251, v[210:213] offset:192
	s_mov_b64 exec, -1
	s_waitcnt vmcnt(11)
	v_mul_f32_e32 v194, v16, v148
	v_mul_f32_e32 v195, v16, v149
	v_mul_f32_e32 v196, v16, v150
	v_mul_f32_e32 v197, v16, v151
	v_fmac_f32_e32 v194, v17, v154
	v_fmac_f32_e32 v195, v17, v155
	v_fmac_f32_e32 v196, v17, v156
	v_fmac_f32_e32 v197, v17, v157
	v_fmac_f32_e32 v194, v18, v158
	v_fmac_f32_e32 v195, v18, v159
	v_fmac_f32_e32 v196, v18, v160
	v_fmac_f32_e32 v197, v18, v161
	v_fmac_f32_e32 v194, v19, v162
	v_fmac_f32_e32 v195, v19, v163
	v_fmac_f32_e32 v196, v19, v164
	v_fmac_f32_e32 v197, v19, v165
	v_add_f32_dpp v194, v194, v194 row_ror:8 row_mask:0xf bank_mask:0xf
	v_add_f32_dpp v195, v195, v195 row_ror:8 row_mask:0xf bank_mask:0xf
	v_add_f32_dpp v196, v196, v196 row_ror:8 row_mask:0xf bank_mask:0xf
	v_add_f32_dpp v197, v197, v197 row_ror:8 row_mask:0xf bank_mask:0xf
	v_add_f32_dpp v194, v194, v194 row_ror:4 row_mask:0xf bank_mask:0xf
	v_add_f32_dpp v195, v195, v195 row_ror:4 row_mask:0xf bank_mask:0xf
	v_add_f32_dpp v196, v196, v196 row_ror:4 row_mask:0xf bank_mask:0xf
	v_add_f32_dpp v197, v197, v197 row_ror:4 row_mask:0xf bank_mask:0xf
	v_add_f32_dpp v194, v194, v194 row_ror:2 row_mask:0xf bank_mask:0xf
	v_add_f32_dpp v195, v195, v195 row_ror:2 row_mask:0xf bank_mask:0xf
	v_add_f32_dpp v196, v196, v196 row_ror:2 row_mask:0xf bank_mask:0xf
	v_add_f32_dpp v197, v197, v197 row_ror:2 row_mask:0xf bank_mask:0xf
	v_add_f32_dpp v194, v194, v194 row_ror:1 row_mask:0xf bank_mask:0xf
	v_add_f32_dpp v195, v195, v195 row_ror:1 row_mask:0xf bank_mask:0xf
	v_add_f32_dpp v196, v196, v196 row_ror:1 row_mask:0xf bank_mask:0xf
	v_add_f32_dpp v197, v197, v197 row_ror:1 row_mask:0xf bank_mask:0xf
	s_mov_b64 exec, s[2:3]
	ds_write_b128 v251, v[194:197] offset:256
	s_mov_b64 exec, -1
	s_waitcnt vmcnt(10)
	v_mul_f32_e32 v210, v20, v148
	v_mul_f32_e32 v211, v20, v149
	v_mul_f32_e32 v212, v20, v150
	v_mul_f32_e32 v213, v20, v151
	v_fmac_f32_e32 v210, v21, v154
	v_fmac_f32_e32 v211, v21, v155
	v_fmac_f32_e32 v212, v21, v156
	v_fmac_f32_e32 v213, v21, v157
	v_fmac_f32_e32 v210, v22, v158
	v_fmac_f32_e32 v211, v22, v159
	v_fmac_f32_e32 v212, v22, v160
	v_fmac_f32_e32 v213, v22, v161
	v_fmac_f32_e32 v210, v23, v162
	v_fmac_f32_e32 v211, v23, v163
	v_fmac_f32_e32 v212, v23, v164
	v_fmac_f32_e32 v213, v23, v165
	v_add_f32_dpp v210, v210, v210 row_ror:8 row_mask:0xf bank_mask:0xf
	v_add_f32_dpp v211, v211, v211 row_ror:8 row_mask:0xf bank_mask:0xf
	v_add_f32_dpp v212, v212, v212 row_ror:8 row_mask:0xf bank_mask:0xf
	v_add_f32_dpp v213, v213, v213 row_ror:8 row_mask:0xf bank_mask:0xf
	v_add_f32_dpp v210, v210, v210 row_ror:4 row_mask:0xf bank_mask:0xf
	v_add_f32_dpp v211, v211, v211 row_ror:4 row_mask:0xf bank_mask:0xf
	v_add_f32_dpp v212, v212, v212 row_ror:4 row_mask:0xf bank_mask:0xf
	v_add_f32_dpp v213, v213, v213 row_ror:4 row_mask:0xf bank_mask:0xf
	v_add_f32_dpp v210, v210, v210 row_ror:2 row_mask:0xf bank_mask:0xf
	v_add_f32_dpp v211, v211, v211 row_ror:2 row_mask:0xf bank_mask:0xf
	v_add_f32_dpp v212, v212, v212 row_ror:2 row_mask:0xf bank_mask:0xf
	v_add_f32_dpp v213, v213, v213 row_ror:2 row_mask:0xf bank_mask:0xf
	v_add_f32_dpp v210, v210, v210 row_ror:1 row_mask:0xf bank_mask:0xf
	v_add_f32_dpp v211, v211, v211 row_ror:1 row_mask:0xf bank_mask:0xf
	v_add_f32_dpp v212, v212, v212 row_ror:1 row_mask:0xf bank_mask:0xf
	v_add_f32_dpp v213, v213, v213 row_ror:1 row_mask:0xf bank_mask:0xf
	s_mov_b64 exec, s[2:3]
	ds_write_b128 v251, v[210:213] offset:320
	s_mov_b64 exec, -1
	s_waitcnt vmcnt(9)
; template <int L, int N> DEVQ void filt_item(const Params& P, LAS unsigned char* lds, const float* H3v, int d, cf* specd, float* cornerd) {
;     ...
;         for (int i4 = 0; i4 < 16; ++i4) hv[i4] = hr[i4];
; #pragma unroll
;         for (int i4 = 0; i4 < 16; ++i4) { if ((i4 & 3) == 0) asm volatile("" ::: "memory");
;             acc += hv[i4].x * wc4[4 * i4] + hv[i4].y * wc4[4 * i4 + 1] + hv[i4].z * wc4[4 * i4 + 2] + hv[i4].w * wc4[4 * i4 + 3]; }
	v_mul_f32_e32 v194, v24, v148
	v_mul_f32_e32 v195, v24, v149
	v_mul_f32_e32 v196, v24, v150
	v_mul_f32_e32 v197, v24, v151
	v_fmac_f32_e32 v194, v25, v154
	v_fmac_f32_e32 v195, v25, v155
	v_fmac_f32_e32 v196, v25, v156
	v_fmac_f32_e32 v197, v25, v157
	v_fmac_f32_e32 v194, v26, v158
	v_fmac_f32_e32 v195, v26, v159
	v_fmac_f32_e32 v196, v26, v160
	v_fmac_f32_e32 v197, v26, v161
	v_fmac_f32_e32 v194, v27, v162
	v_fmac_f32_e32 v195, v27, v163
	v_fmac_f32_e32 v196, v27, v164
	v_fmac_f32_e32 v197, v27, v165
	v_add_f32_dpp v194, v194, v194 row_ror:8 row_mask:0xf bank_mask:0xf
	v_add_f32_dpp v195, v195, v195 row_ror:8 row_mask:0xf bank_mask:0xf
	v_add_f32_dpp v196, v196, v196 row_ror:8 row_mask:0xf bank_mask:0xf
	v_add_f32_dpp v197, v197, v197 row_ror:8 row_mask:0xf bank_mask:0xf
	v_add_f32_dpp v194, v194, v194 row_ror:4 row_mask:0xf bank_mask:0xf
	v_add_f32_dpp v195, v195, v195 row_ror:4 row_mask:0xf bank_mask:0xf
	v_add_f32_dpp v196, v196, v196 row_ror:4 row_mask:0xf bank_mask:0xf
	v_add_f32_dpp v197, v197, v197 row_ror:4 row_mask:0xf bank_mask:0xf
	v_add_f32_dpp v194, v194, v194 row_ror:2 row_mask:0xf bank_mask:0xf
	v_add_f32_dpp v195, v195, v195 row_ror:2 row_mask:0xf bank_mask:0xf
	v_add_f32_dpp v196, v196, v196 row_ror:2 row_mask:0xf bank_mask:0xf
	v_add_f32_dpp v197, v197, v197 row_ror:2 row_mask:0xf bank_mask:0xf
	v_add_f32_dpp v194, v194, v194 row_ror:1 row_mask:0xf bank_mask:0xf
	v_add_f32_dpp v195, v195, v195 row_ror:1 row_mask:0xf bank_mask:0xf
	v_add_f32_dpp v196, v196, v196 row_ror:1 row_mask:0xf bank_mask:0xf
	v_add_f32_dpp v197, v197, v197 row_ror:1 row_mask:0xf bank_mask:0xf
	s_mov_b64 exec, s[2:3]
	ds_write_b128 v251, v[194:197] offset:384
	s_mov_b64 exec, -1
	s_waitcnt vmcnt(8)
	v_mul_f32_e32 v210, v28, v148
	v_mul_f32_e32 v211, v28, v149
	v_mul_f32_e32 v212, v28, v150
	v_mul_f32_e32 v213, v28, v151
	v_fmac_f32_e32 v210, v29, v154
	v_fmac_f32_e32 v211, v29, v155
	v_fmac_f32_e32 v212, v29, v156
	v_fmac_f32_e32 v213, v29, v157
	v_fmac_f32_e32 v210, v30, v158
	v_fmac_f32_e32 v211, v30, v159
	v_fmac_f32_e32 v212, v30, v160
	v_fmac_f32_e32 v213, v30, v161
	v_fmac_f32_e32 v210, v31, v162
	v_fmac_f32_e32 v211, v31, v163
	v_fmac_f32_e32 v212, v31, v164
	v_fmac_f32_e32 v213, v31, v165
	v_add_f32_dpp v210, v210, v210 row_ror:8 row_mask:0xf bank_mask:0xf
	v_add_f32_dpp v211, v211, v211 row_ror:8 row_mask:0xf bank_mask:0xf
	v_add_f32_dpp v212, v212, v212 row_ror:8 row_mask:0xf bank_mask:0xf
	v_add_f32_dpp v213, v213, v213 row_ror:8 row_mask:0xf bank_mask:0xf
	v_add_f32_dpp v210, v210, v210 row_ror:4 row_mask:0xf bank_mask:0xf
	v_add_f32_dpp v211, v211, v211 row_ror:4 row_mask:0xf bank_mask:0xf
	v_add_f32_dpp v212, v212, v212 row_ror:4 row_mask:0xf bank_mask:0xf
	v_add_f32_dpp v213, v213, v213 row_ror:4 row_mask:0xf bank_mask:0xf
	v_add_f32_dpp v210, v210, v210 row_ror:2 row_mask:0xf bank_mask:0xf
	v_add_f32_dpp v211, v211, v211 row_ror:2 row_mask:0xf bank_mask:0xf
	v_add_f32_dpp v212, v212, v212 row_ror:2 row_mask:0xf bank_mask:0xf
	v_add_f32_dpp v213, v213, v213 row_ror:2 row_mask:0xf bank_mask:0xf
	v_add_f32_dpp v210, v210, v210 row_ror:1 row_mask:0xf bank_mask:0xf
	v_add_f32_dpp v211, v211, v211 row_ror:1 row_mask:0xf bank_mask:0xf
	v_add_f32_dpp v212, v212, v212 row_ror:1 row_mask:0xf bank_mask:0xf
	v_add_f32_dpp v213, v213, v213 row_ror:1 row_mask:0xf bank_mask:0xf
	s_mov_b64 exec, s[2:3]
	ds_write_b128 v251, v[210:213] offset:448
	s_mov_b64 exec, -1
	s_waitcnt vmcnt(7)
	v_mul_f32_e32 v194, v32, v148
	v_mul_f32_e32 v195, v32, v149
	v_mul_f32_e32 v196, v32, v150
	v_mul_f32_e32 v197, v32, v151
	v_fmac_f32_e32 v194, v33, v154
	v_fmac_f32_e32 v195, v33, v155
	v_fmac_f32_e32 v196, v33, v156
	v_fmac_f32_e32 v197, v33, v157
	v_fmac_f32_e32 v194, v34, v158
	v_fmac_f32_e32 v195, v34, v159
	v_fmac_f32_e32 v196, v34, v160
	v_fmac_f32_e32 v197, v34, v161
	v_fmac_f32_e32 v194, v35, v162
	v_fmac_f32_e32 v195, v35, v163
	v_fmac_f32_e32 v196, v35, v164
	v_fmac_f32_e32 v197, v35, v165
	v_add_f32_dpp v194, v194, v194 row_ror:8 row_mask:0xf bank_mask:0xf
	v_add_f32_dpp v195, v195, v195 row_ror:8 row_mask:0xf bank_mask:0xf
	v_add_f32_dpp v196, v196, v196 row_ror:8 row_mask:0xf bank_mask:0xf
	v_add_f32_dpp v197, v197, v197 row_ror:8 row_mask:0xf bank_mask:0xf
	v_add_f32_dpp v194, v194, v194 row_ror:4 row_mask:0xf bank_mask:0xf
	v_add_f32_dpp v195, v195, v195 row_ror:4 row_mask:0xf bank_mask:0xf
	v_add_f32_dpp v196, v196, v196 row_ror:4 row_mask:0xf bank_mask:0xf
	v_add_f32_dpp v197, v197, v197 row_ror:4 row_mask:0xf bank_mask:0xf
	v_add_f32_dpp v194, v194, v194 row_ror:2 row_mask:0xf bank_mask:0xf
	v_add_f32_dpp v195, v195, v195 row_ror:2 row_mask:0xf bank_mask:0xf
	v_add_f32_dpp v196, v196, v196 row_ror:2 row_mask:0xf bank_mask:0xf
	v_add_f32_dpp v197, v197, v197 row_ror:2 row_mask:0xf bank_mask:0xf
	v_add_f32_dpp v194, v194, v194 row_ror:1 row_mask:0xf bank_mask:0xf
	v_add_f32_dpp v195, v195, v195 row_ror:1 row_mask:0xf bank_mask:0xf
	v_add_f32_dpp v196, v196, v196 row_ror:1 row_mask:0xf bank_mask:0xf
	v_add_f32_dpp v197, v197, v197 row_ror:1 row_mask:0xf bank_mask:0xf
	s_mov_b64 exec, s[2:3]
	ds_write_b128 v251, v[194:197] offset:512
	s_mov_b64 exec, -1
	s_waitcnt vmcnt(6)
; template <int L, int N> DEVQ void filt_item(const Params& P, LAS unsigned char* lds, const float* H3v, int d, cf* specd, float* cornerd) {
;     ...
;         for (int i4 = 0; i4 < 16; ++i4) hv[i4] = hr[i4];
; #pragma unroll
;         for (int i4 = 0; i4 < 16; ++i4) { if ((i4 & 3) == 0) asm volatile("" ::: "memory");
;             acc += hv[i4].x * wc4[4 * i4] + hv[i4].y * wc4[4 * i4 + 1] + hv[i4].z * wc4[4 * i4 + 2] + hv[i4].w * wc4[4 * i4 + 3]; }
	v_mul_f32_e32 v210, v36, v148
	v_mul_f32_e32 v211, v36, v149
	v_mul_f32_e32 v212, v36, v150
	v_mul_f32_e32 v213, v36, v151
	v_fmac_f32_e32 v210, v37, v154
	v_fmac_f32_e32 v211, v37, v155
	v_fmac_f32_e32 v212, v37, v156
	v_fmac_f32_e32 v213, v37, v157
	v_fmac_f32_e32 v210, v38, v158
	v_fmac_f32_e32 v211, v38, v159
	v_fmac_f32_e32 v212, v38, v160
	v_fmac_f32_e32 v213, v38, v161
	v_fmac_f32_e32 v210, v39, v162
	v_fmac_f32_e32 v211, v39, v163
	v_fmac_f32_e32 v212, v39, v164
	v_fmac_f32_e32 v213, v39, v165
	v_add_f32_dpp v210, v210, v210 row_ror:8 row_mask:0xf bank_mask:0xf
	v_add_f32_dpp v211, v211, v211 row_ror:8 row_mask:0xf bank_mask:0xf
	v_add_f32_dpp v212, v212, v212 row_ror:8 row_mask:0xf bank_mask:0xf
	v_add_f32_dpp v213, v213, v213 row_ror:8 row_mask:0xf bank_mask:0xf
	v_add_f32_dpp v210, v210, v210 row_ror:4 row_mask:0xf bank_mask:0xf
	v_add_f32_dpp v211, v211, v211 row_ror:4 row_mask:0xf bank_mask:0xf
	v_add_f32_dpp v212, v212, v212 row_ror:4 row_mask:0xf bank_mask:0xf
	v_add_f32_dpp v213, v213, v213 row_ror:4 row_mask:0xf bank_mask:0xf
	v_add_f32_dpp v210, v210, v210 row_ror:2 row_mask:0xf bank_mask:0xf
	v_add_f32_dpp v211, v211, v211 row_ror:2 row_mask:0xf bank_mask:0xf
	v_add_f32_dpp v212, v212, v212 row_ror:2 row_mask:0xf bank_mask:0xf
	v_add_f32_dpp v213, v213, v213 row_ror:2 row_mask:0xf bank_mask:0xf
	v_add_f32_dpp v210, v210, v210 row_ror:1 row_mask:0xf bank_mask:0xf
	v_add_f32_dpp v211, v211, v211 row_ror:1 row_mask:0xf bank_mask:0xf
	v_add_f32_dpp v212, v212, v212 row_ror:1 row_mask:0xf bank_mask:0xf
	v_add_f32_dpp v213, v213, v213 row_ror:1 row_mask:0xf bank_mask:0xf
	s_mov_b64 exec, s[2:3]
	ds_write_b128 v251, v[210:213] offset:576
	s_mov_b64 exec, -1
	s_waitcnt vmcnt(5)
	v_mul_f32_e32 v194, v40, v148
	v_mul_f32_e32 v195, v40, v149
	v_mul_f32_e32 v196, v40, v150
	v_mul_f32_e32 v197, v40, v151
	v_fmac_f32_e32 v194, v41, v154
	v_fmac_f32_e32 v195, v41, v155
	v_fmac_f32_e32 v196, v41, v156
	v_fmac_f32_e32 v197, v41, v157
	v_fmac_f32_e32 v194, v42, v158
	v_fmac_f32_e32 v195, v42, v159
	v_fmac_f32_e32 v196, v42, v160
	v_fmac_f32_e32 v197, v42, v161
	v_fmac_f32_e32 v194, v43, v162
	v_fmac_f32_e32 v195, v43, v163
	v_fmac_f32_e32 v196, v43, v164
	v_fmac_f32_e32 v197, v43, v165
	v_add_f32_dpp v194, v194, v194 row_ror:8 row_mask:0xf bank_mask:0xf
	v_add_f32_dpp v195, v195, v195 row_ror:8 row_mask:0xf bank_mask:0xf
	v_add_f32_dpp v196, v196, v196 row_ror:8 row_mask:0xf bank_mask:0xf
	v_add_f32_dpp v197, v197, v197 row_ror:8 row_mask:0xf bank_mask:0xf
	v_add_f32_dpp v194, v194, v194 row_ror:4 row_mask:0xf bank_mask:0xf
	v_add_f32_dpp v195, v195, v195 row_ror:4 row_mask:0xf bank_mask:0xf
	v_add_f32_dpp v196, v196, v196 row_ror:4 row_mask:0xf bank_mask:0xf
	v_add_f32_dpp v197, v197, v197 row_ror:4 row_mask:0xf bank_mask:0xf
	v_add_f32_dpp v194, v194, v194 row_ror:2 row_mask:0xf bank_mask:0xf
	v_add_f32_dpp v195, v195, v195 row_ror:2 row_mask:0xf bank_mask:0xf
	v_add_f32_dpp v196, v196, v196 row_ror:2 row_mask:0xf bank_mask:0xf
	v_add_f32_dpp v197, v197, v197 row_ror:2 row_mask:0xf bank_mask:0xf
	v_add_f32_dpp v194, v194, v194 row_ror:1 row_mask:0xf bank_mask:0xf
	v_add_f32_dpp v195, v195, v195 row_ror:1 row_mask:0xf bank_mask:0xf
	v_add_f32_dpp v196, v196, v196 row_ror:1 row_mask:0xf bank_mask:0xf
	v_add_f32_dpp v197, v197, v197 row_ror:1 row_mask:0xf bank_mask:0xf
	s_mov_b64 exec, s[2:3]
	ds_write_b128 v251, v[194:197] offset:640
	s_mov_b64 exec, -1
	s_waitcnt vmcnt(4)
	v_mul_f32_e32 v210, v44, v148
	v_mul_f32_e32 v211, v44, v149
	v_mul_f32_e32 v212, v44, v150
	v_mul_f32_e32 v213, v44, v151
	v_fmac_f32_e32 v210, v45, v154
	v_fmac_f32_e32 v211, v45, v155
	v_fmac_f32_e32 v212, v45, v156
	v_fmac_f32_e32 v213, v45, v157
	v_fmac_f32_e32 v210, v46, v158
	v_fmac_f32_e32 v211, v46, v159
	v_fmac_f32_e32 v212, v46, v160
	v_fmac_f32_e32 v213, v46, v161
	v_fmac_f32_e32 v210, v47, v162
	v_fmac_f32_e32 v211, v47, v163
	v_fmac_f32_e32 v212, v47, v164
	v_fmac_f32_e32 v213, v47, v165
	v_add_f32_dpp v210, v210, v210 row_ror:8 row_mask:0xf bank_mask:0xf
	v_add_f32_dpp v211, v211, v211 row_ror:8 row_mask:0xf bank_mask:0xf
	v_add_f32_dpp v212, v212, v212 row_ror:8 row_mask:0xf bank_mask:0xf
	v_add_f32_dpp v213, v213, v213 row_ror:8 row_mask:0xf bank_mask:0xf
	v_add_f32_dpp v210, v210, v210 row_ror:4 row_mask:0xf bank_mask:0xf
	v_add_f32_dpp v211, v211, v211 row_ror:4 row_mask:0xf bank_mask:0xf
	v_add_f32_dpp v212, v212, v212 row_ror:4 row_mask:0xf bank_mask:0xf
	v_add_f32_dpp v213, v213, v213 row_ror:4 row_mask:0xf bank_mask:0xf
	v_add_f32_dpp v210, v210, v210 row_ror:2 row_mask:0xf bank_mask:0xf
	v_add_f32_dpp v211, v211, v211 row_ror:2 row_mask:0xf bank_mask:0xf
	v_add_f32_dpp v212, v212, v212 row_ror:2 row_mask:0xf bank_mask:0xf
	v_add_f32_dpp v213, v213, v213 row_ror:2 row_mask:0xf bank_mask:0xf
	v_add_f32_dpp v210, v210, v210 row_ror:1 row_mask:0xf bank_mask:0xf
	v_add_f32_dpp v211, v211, v211 row_ror:1 row_mask:0xf bank_mask:0xf
	v_add_f32_dpp v212, v212, v212 row_ror:1 row_mask:0xf bank_mask:0xf
	v_add_f32_dpp v213, v213, v213 row_ror:1 row_mask:0xf bank_mask:0xf
	s_mov_b64 exec, s[2:3]
	ds_write_b128 v251, v[210:213] offset:704
	s_mov_b64 exec, -1
	s_waitcnt vmcnt(3)
; template <int L, int N> DEVQ void filt_item(const Params& P, LAS unsigned char* lds, const float* H3v, int d, cf* specd, float* cornerd) {
;     ...
;         for (int i4 = 0; i4 < 16; ++i4) hv[i4] = hr[i4];
; #pragma unroll
;         for (int i4 = 0; i4 < 16; ++i4) { if ((i4 & 3) == 0) asm volatile("" ::: "memory");
;             acc += hv[i4].x * wc4[4 * i4] + hv[i4].y * wc4[4 * i4 + 1] + hv[i4].z * wc4[4 * i4 + 2] + hv[i4].w * wc4[4 * i4 + 3]; }
	v_mul_f32_e32 v194, v48, v148
	v_mul_f32_e32 v195, v48, v149
	v_mul_f32_e32 v196, v48, v150
	v_mul_f32_e32 v197, v48, v151
	v_fmac_f32_e32 v194, v49, v154
	v_fmac_f32_e32 v195, v49, v155
	v_fmac_f32_e32 v196, v49, v156
	v_fmac_f32_e32 v197, v49, v157
	v_fmac_f32_e32 v194, v50, v158
	v_fmac_f32_e32 v195, v50, v159
	v_fmac_f32_e32 v196, v50, v160
	v_fmac_f32_e32 v197, v50, v161
	v_fmac_f32_e32 v194, v51, v162
	v_fmac_f32_e32 v195, v51, v163
	v_fmac_f32_e32 v196, v51, v164
	v_fmac_f32_e32 v197, v51, v165
	v_add_f32_dpp v194, v194, v194 row_ror:8 row_mask:0xf bank_mask:0xf
	v_add_f32_dpp v195, v195, v195 row_ror:8 row_mask:0xf bank_mask:0xf
	v_add_f32_dpp v196, v196, v196 row_ror:8 row_mask:0xf bank_mask:0xf
	v_add_f32_dpp v197, v197, v197 row_ror:8 row_mask:0xf bank_mask:0xf
	v_add_f32_dpp v194, v194, v194 row_ror:4 row_mask:0xf bank_mask:0xf
	v_add_f32_dpp v195, v195, v195 row_ror:4 row_mask:0xf bank_mask:0xf
	v_add_f32_dpp v196, v196, v196 row_ror:4 row_mask:0xf bank_mask:0xf
	v_add_f32_dpp v197, v197, v197 row_ror:4 row_mask:0xf bank_mask:0xf
	v_add_f32_dpp v194, v194, v194 row_ror:2 row_mask:0xf bank_mask:0xf
	v_add_f32_dpp v195, v195, v195 row_ror:2 row_mask:0xf bank_mask:0xf
	v_add_f32_dpp v196, v196, v196 row_ror:2 row_mask:0xf bank_mask:0xf
	v_add_f32_dpp v197, v197, v197 row_ror:2 row_mask:0xf bank_mask:0xf
	v_add_f32_dpp v194, v194, v194 row_ror:1 row_mask:0xf bank_mask:0xf
	v_add_f32_dpp v195, v195, v195 row_ror:1 row_mask:0xf bank_mask:0xf
	v_add_f32_dpp v196, v196, v196 row_ror:1 row_mask:0xf bank_mask:0xf
	v_add_f32_dpp v197, v197, v197 row_ror:1 row_mask:0xf bank_mask:0xf
	s_mov_b64 exec, s[2:3]
	ds_write_b128 v251, v[194:197] offset:768
	s_mov_b64 exec, -1
	s_waitcnt vmcnt(2)
	v_mul_f32_e32 v210, v52, v148
	v_mul_f32_e32 v211, v52, v149
	v_mul_f32_e32 v212, v52, v150
	v_mul_f32_e32 v213, v52, v151
	v_fmac_f32_e32 v210, v53, v154
	v_fmac_f32_e32 v211, v53, v155
	v_fmac_f32_e32 v212, v53, v156
	v_fmac_f32_e32 v213, v53, v157
	v_fmac_f32_e32 v210, v54, v158
	v_fmac_f32_e32 v211, v54, v159
	v_fmac_f32_e32 v212, v54, v160
	v_fmac_f32_e32 v213, v54, v161
	v_fmac_f32_e32 v210, v55, v162
	v_fmac_f32_e32 v211, v55, v163
	v_fmac_f32_e32 v212, v55, v164
	v_fmac_f32_e32 v213, v55, v165
	v_add_f32_dpp v210, v210, v210 row_ror:8 row_mask:0xf bank_mask:0xf
	v_add_f32_dpp v211, v211, v211 row_ror:8 row_mask:0xf bank_mask:0xf
	v_add_f32_dpp v212, v212, v212 row_ror:8 row_mask:0xf bank_mask:0xf
	v_add_f32_dpp v213, v213, v213 row_ror:8 row_mask:0xf bank_mask:0xf
	v_add_f32_dpp v210, v210, v210 row_ror:4 row_mask:0xf bank_mask:0xf
	v_add_f32_dpp v211, v211, v211 row_ror:4 row_mask:0xf bank_mask:0xf
	v_add_f32_dpp v212, v212, v212 row_ror:4 row_mask:0xf bank_mask:0xf
	v_add_f32_dpp v213, v213, v213 row_ror:4 row_mask:0xf bank_mask:0xf
	v_add_f32_dpp v210, v210, v210 row_ror:2 row_mask:0xf bank_mask:0xf
	v_add_f32_dpp v211, v211, v211 row_ror:2 row_mask:0xf bank_mask:0xf
	v_add_f32_dpp v212, v212, v212 row_ror:2 row_mask:0xf bank_mask:0xf
	v_add_f32_dpp v213, v213, v213 row_ror:2 row_mask:0xf bank_mask:0xf
	v_add_f32_dpp v210, v210, v210 row_ror:1 row_mask:0xf bank_mask:0xf
	v_add_f32_dpp v211, v211, v211 row_ror:1 row_mask:0xf bank_mask:0xf
	v_add_f32_dpp v212, v212, v212 row_ror:1 row_mask:0xf bank_mask:0xf
	v_add_f32_dpp v213, v213, v213 row_ror:1 row_mask:0xf bank_mask:0xf
	s_mov_b64 exec, s[2:3]
	ds_write_b128 v251, v[210:213] offset:832
	s_mov_b64 exec, -1
	s_waitcnt vmcnt(1)
; template <int L, int N> DEVQ void filt_item(const Params& P, LAS unsigned char* lds, const float* H3v, int d, cf* specd, float* cornerd) {
;     ...
;         for (int i4 = 0; i4 < 16; ++i4) hv[i4] = hr[i4];
; #pragma unroll
;         for (int i4 = 0; i4 < 16; ++i4) { if ((i4 & 3) == 0) asm volatile("" ::: "memory");
;             acc += hv[i4].x * wc4[4 * i4] + hv[i4].y * wc4[4 * i4 + 1] + hv[i4].z * wc4[4 * i4 + 2] + hv[i4].w * wc4[4 * i4 + 3]; }
;         const float dec = expf(-((float)k / (float)(L - 1)) * delta);
;         acc *= dec;
;         if (k <= N / 2) X[swz(k)] = cf{acc.x * invN, acc.z * invN};
;         if (k >= 1 && k < N / 2) X[swz(N - k)] = cf{acc.y * invN, acc.w * invN};
	v_mul_f32_e32 v194, v56, v148
	v_mul_f32_e32 v195, v56, v149
	v_mul_f32_e32 v196, v56, v150
	v_mul_f32_e32 v197, v56, v151
	v_fmac_f32_e32 v194, v57, v154
	v_fmac_f32_e32 v195, v57, v155
	v_fmac_f32_e32 v196, v57, v156
	v_fmac_f32_e32 v197, v57, v157
	v_fmac_f32_e32 v194, v58, v158
	v_fmac_f32_e32 v195, v58, v159
	v_fmac_f32_e32 v196, v58, v160
	v_fmac_f32_e32 v197, v58, v161
	v_fmac_f32_e32 v194, v59, v162
	v_fmac_f32_e32 v195, v59, v163
	v_fmac_f32_e32 v196, v59, v164
	v_fmac_f32_e32 v197, v59, v165
	v_add_f32_dpp v194, v194, v194 row_ror:8 row_mask:0xf bank_mask:0xf
	v_add_f32_dpp v195, v195, v195 row_ror:8 row_mask:0xf bank_mask:0xf
	v_add_f32_dpp v196, v196, v196 row_ror:8 row_mask:0xf bank_mask:0xf
	v_add_f32_dpp v197, v197, v197 row_ror:8 row_mask:0xf bank_mask:0xf
	v_add_f32_dpp v194, v194, v194 row_ror:4 row_mask:0xf bank_mask:0xf
	v_add_f32_dpp v195, v195, v195 row_ror:4 row_mask:0xf bank_mask:0xf
	v_add_f32_dpp v196, v196, v196 row_ror:4 row_mask:0xf bank_mask:0xf
	v_add_f32_dpp v197, v197, v197 row_ror:4 row_mask:0xf bank_mask:0xf
	v_add_f32_dpp v194, v194, v194 row_ror:2 row_mask:0xf bank_mask:0xf
	v_add_f32_dpp v195, v195, v195 row_ror:2 row_mask:0xf bank_mask:0xf
	v_add_f32_dpp v196, v196, v196 row_ror:2 row_mask:0xf bank_mask:0xf
	v_add_f32_dpp v197, v197, v197 row_ror:2 row_mask:0xf bank_mask:0xf
	v_add_f32_dpp v194, v194, v194 row_ror:1 row_mask:0xf bank_mask:0xf
	v_add_f32_dpp v195, v195, v195 row_ror:1 row_mask:0xf bank_mask:0xf
	v_add_f32_dpp v196, v196, v196 row_ror:1 row_mask:0xf bank_mask:0xf
	v_add_f32_dpp v197, v197, v197 row_ror:1 row_mask:0xf bank_mask:0xf
	s_mov_b64 exec, s[2:3]
	ds_write_b128 v251, v[194:197] offset:896
	s_mov_b64 exec, -1
	s_waitcnt vmcnt(0)
	v_mul_f32_e32 v210, v60, v148
	v_mul_f32_e32 v211, v60, v149
	v_mul_f32_e32 v212, v60, v150
	v_mul_f32_e32 v213, v60, v151
	v_fmac_f32_e32 v210, v61, v154
	v_fmac_f32_e32 v211, v61, v155
	v_fmac_f32_e32 v212, v61, v156
	v_fmac_f32_e32 v213, v61, v157
	v_fmac_f32_e32 v210, v62, v158
	v_fmac_f32_e32 v211, v62, v159
	v_fmac_f32_e32 v212, v62, v160
	v_fmac_f32_e32 v213, v62, v161
	v_fmac_f32_e32 v210, v63, v162
	v_fmac_f32_e32 v211, v63, v163
	v_fmac_f32_e32 v212, v63, v164
	v_fmac_f32_e32 v213, v63, v165
	v_add_f32_dpp v210, v210, v210 row_ror:8 row_mask:0xf bank_mask:0xf
	v_add_f32_dpp v211, v211, v211 row_ror:8 row_mask:0xf bank_mask:0xf
	v_add_f32_dpp v212, v212, v212 row_ror:8 row_mask:0xf bank_mask:0xf
	v_add_f32_dpp v213, v213, v213 row_ror:8 row_mask:0xf bank_mask:0xf
	v_add_f32_dpp v210, v210, v210 row_ror:4 row_mask:0xf bank_mask:0xf
	v_add_f32_dpp v211, v211, v211 row_ror:4 row_mask:0xf bank_mask:0xf
	v_add_f32_dpp v212, v212, v212 row_ror:4 row_mask:0xf bank_mask:0xf
	v_add_f32_dpp v213, v213, v213 row_ror:4 row_mask:0xf bank_mask:0xf
	v_add_f32_dpp v210, v210, v210 row_ror:2 row_mask:0xf bank_mask:0xf
	v_add_f32_dpp v211, v211, v211 row_ror:2 row_mask:0xf bank_mask:0xf
	v_add_f32_dpp v212, v212, v212 row_ror:2 row_mask:0xf bank_mask:0xf
	v_add_f32_dpp v213, v213, v213 row_ror:2 row_mask:0xf bank_mask:0xf
	v_add_f32_dpp v210, v210, v210 row_ror:1 row_mask:0xf bank_mask:0xf
	v_add_f32_dpp v211, v211, v211 row_ror:1 row_mask:0xf bank_mask:0xf
	v_add_f32_dpp v212, v212, v212 row_ror:1 row_mask:0xf bank_mask:0xf
	v_add_f32_dpp v213, v213, v213 row_ror:1 row_mask:0xf bank_mask:0xf
	s_mov_b64 exec, s[2:3]
	ds_write_b128 v251, v[210:213] offset:960
	s_mov_b64 exec, -1
	s_waitcnt lgkmcnt(0)
	ds_read_b128 v[0:3], v250
	v_cvt_f32_i32_e32 v4, v75
	s_waitcnt lgkmcnt(0)
	s_mov_b64 exec, s[20:21]
	v_div_scale_f32 v5, s[2:3], s23, s23, v4
	v_rcp_f32_e32 v6, v5
	s_mov_b32 s2, 0xc2ce8ed0
	v_fma_f32 v7, -v5, v6, 1.0
	v_fmac_f32_e32 v6, v7, v6
	v_div_scale_f32 v7, vcc, v4, s23, v4
	v_mul_f32_e32 v8, v7, v6
	v_fma_f32 v9, -v5, v8, v7
	v_fmac_f32_e32 v8, v9, v6
	v_fma_f32 v5, -v5, v8, v7
	v_div_fmas_f32 v5, v5, v6, v8
	v_div_fixup_f32 v4, v5, s23, v4
	v_mul_f32_e64 v4, |v74|, v4
	v_mul_f32_e32 v5, 0x3fb8aa3b, v4
	v_fma_f32 v6, v4, s18, -v5
	v_rndne_f32_e32 v7, v5
	v_fmac_f32_e32 v6, 0x32a5705f, v4
	v_sub_f32_e32 v5, v5, v7
	v_add_f32_e32 v5, v5, v6
	v_exp_f32_e32 v5, v5
	v_cvt_i32_f32_e32 v6, v7
	v_cmp_ngt_f32_e32 vcc, s2, v4
	s_mov_b32 s2, 0x42b17218
	v_ldexp_f32 v5, v5, v6
	v_cndmask_b32_e32 v5, 0, v5, vcc
	v_cmp_nlt_f32_e32 vcc, s2, v4
	s_movk_i32 s2, 0x2001
	s_nop 0
	v_cndmask_b32_e32 v4, v188, v5, vcc
	v_pk_mul_f32 v[0:1], v[4:5], v[0:1] op_sel_hi:[0,1]
	v_pk_mul_f32 v[2:3], v[4:5], v[2:3] op_sel_hi:[0,1]
	v_cmp_gt_i32_e32 vcc, s2, v75
	s_and_saveexec_b64 s[20:21], vcc
	s_cbranch_execz .LBB0_629
	v_ashrrev_i32_e32 v6, 5, v75
	v_lshlrev_b32_e32 v7, 2, v6
	v_and_b32_e32 v7, 28, v7
	v_and_b32_e32 v6, 3, v6
	v_mov_b32_e32 v4, v0
	v_mov_b32_e32 v5, v2
	s_mov_b32 s2, 0x38800000
	v_bitop3_b32 v6, v7, v75, v6 bitop3:0x36
	v_pk_mul_f32 v[4:5], v[4:5], s[2:3] op_sel_hi:[1,0]
	v_lshl_add_u32 v6, v6, 3, 0
	ds_write_b64 v6, v[4:5]
